# attention: the next tile's V piece and mask words are requested in front of the tile barrier (their ring slot / registers are provably free there); only the K piece waits for the release
# speedup vs baseline: 1.0026x; 1.0026x over previous
.Lat_qb:
	s_lshl_b32 s9, s2, 2
	s_lshr_b32 s10, s3, 1
	s_add_u32 s10, s10, s9
	s_add_u32 s11, s9, 3
	s_add_u32 s9, s9, 4
	s_lshl_b32 s18, s2, 8
	s_lshl_b32 s19, s3, 5
	s_add_u32 s18, s18, s19
	v_and_b32_e32 v235, 31, v186
	v_bfe_u32 v237, v186, 5, 1
	v_add_u32_e32 v235, s18, v235
	v_lshlrev_b32_e32 v219, 10, v235
	v_mul_u32_u24_e32 v236, 0x2cb0, v235
	v_lshl_add_u32 v220, v237, 4, v236
	v_lshl_add_u32 v197, v237, 3, v236
	global_load_dwordx4 v[102:105], v220, s[4:5] offset:0
	global_load_dwordx4 v[106:109], v220, s[4:5] offset:32
	global_load_dwordx4 v[110:113], v220, s[4:5] offset:64
	global_load_dwordx4 v[114:117], v220, s[4:5] offset:96
	s_mov_b64 s[12:13], s[4:5]
	s_add_i32 m0, s58, 0x0
	s_nop 0
	global_load_lds_dwordx4 v221, s[12:13]
	s_add_i32 m0, s58, 0x8000
	s_nop 0
	global_load_lds_dwordx4 v222, s[12:13]
	s_add_u32 s12, s12, 0xb2c00
	s_addc_u32 s13, s13, 0
	s_add_i32 m0, s58, 0x2000
	s_nop 0
	global_load_lds_dwordx4 v221, s[12:13]
	s_add_u32 s12, s12, 0xb2c00
	s_addc_u32 s13, s13, 0
	s_add_i32 m0, s58, 0x4000
	s_nop 0
	global_load_lds_dwordx4 v221, s[12:13]
	s_add_u32 s12, s12, 0xb2c00
	s_addc_u32 s13, s13, 0
	global_load_dwordx4 v[198:201], v219, s[6:7]
	s_add_i32 m0, s58, 0x6000
	s_nop 0
	global_load_lds_dwordx4 v221, s[12:13]
	s_add_u32 s14, s4, 0xb2c00
	s_addc_u32 s15, s5, 0
	s_add_i32 m0, s58, 0xa000
	s_nop 0
	global_load_lds_dwordx4 v222, s[14:15]
	v_mov_b32_e32 v230, 0xff800000
	v_mov_b32_e32 v231, 0
	v_mov_b32_e32 v0, 0
	v_mov_b32_e32 v1, 0
	v_mov_b32_e32 v2, 0
	v_mov_b32_e32 v3, 0
	v_mov_b32_e32 v4, 0
	v_mov_b32_e32 v5, 0
	v_mov_b32_e32 v6, 0
	v_mov_b32_e32 v7, 0
	v_mov_b32_e32 v8, 0
	v_mov_b32_e32 v9, 0
	v_mov_b32_e32 v10, 0
	v_mov_b32_e32 v11, 0
	v_mov_b32_e32 v12, 0
	v_mov_b32_e32 v13, 0
	v_mov_b32_e32 v14, 0
	v_mov_b32_e32 v15, 0
	v_mov_b32_e32 v16, 0
	v_mov_b32_e32 v17, 0
	v_mov_b32_e32 v18, 0
	v_mov_b32_e32 v19, 0
	v_mov_b32_e32 v20, 0
	v_mov_b32_e32 v21, 0
	v_mov_b32_e32 v22, 0
	v_mov_b32_e32 v23, 0
	v_mov_b32_e32 v24, 0
	v_mov_b32_e32 v25, 0
	v_mov_b32_e32 v26, 0
	v_mov_b32_e32 v27, 0
	v_mov_b32_e32 v28, 0
	v_mov_b32_e32 v29, 0
	v_mov_b32_e32 v30, 0
	v_mov_b32_e32 v31, 0
	s_waitcnt vmcnt(2)
	s_barrier
	ds_read_b128 v[118:121], v223 offset:0
	ds_read_b128 v[122:125], v223 offset:4096
	ds_read_b128 v[126:129], v224 offset:0
	ds_read_b128 v[130:133], v224 offset:4096
	ds_read_b128 v[134:137], v225 offset:0
	ds_read_b128 v[138:141], v225 offset:4096
	ds_read_b128 v[142:145], v226 offset:0
	ds_read_b128 v[146:149], v226 offset:4096
	s_waitcnt lgkmcnt(0)
	s_barrier
	v_mfma_f32_32x32x16_bf16 v[34:49], v[118:121], v[102:105], 0
	v_mfma_f32_32x32x16_bf16 v[50:65], v[122:125], v[102:105], 0
	v_mfma_f32_32x32x16_bf16 v[34:49], v[126:129], v[106:109], v[34:49]
	v_mfma_f32_32x32x16_bf16 v[50:65], v[130:133], v[106:109], v[50:65]
	v_mfma_f32_32x32x16_bf16 v[34:49], v[134:137], v[110:113], v[34:49]
	v_mfma_f32_32x32x16_bf16 v[50:65], v[138:141], v[110:113], v[50:65]
	v_mfma_f32_32x32x16_bf16 v[34:49], v[142:145], v[114:117], v[34:49]
	v_mfma_f32_32x32x16_bf16 v[50:65], v[146:149], v[114:117], v[50:65]
	ds_read_b128 v[118:121], v223 offset:8192
	ds_read_b128 v[122:125], v223 offset:12288
	ds_read_b128 v[126:129], v224 offset:8192
	ds_read_b128 v[130:133], v224 offset:12288
	ds_read_b128 v[134:137], v225 offset:8192
	ds_read_b128 v[138:141], v225 offset:12288
	ds_read_b128 v[142:145], v226 offset:8192
	ds_read_b128 v[146:149], v226 offset:12288
	s_waitcnt lgkmcnt(14)
	s_mov_b32 s8, 0
	s_add_u32 s18, s8, 4
	s_min_u32 s18, s18, s11
	s_mul_i32 s18, s18, 0xb2c00
	s_add_u32 s12, s4, s18
	s_addc_u32 s13, s5, 0
	s_add_u32 s19, s8, 2
	s_min_u32 s19, s19, s11
	s_mul_i32 s18, s19, 0xb2c00
	s_add_u32 s14, s4, s18
	s_addc_u32 s15, s5, 0
	s_lshl_b32 s19, s19, 3
	s_add_u32 s16, s6, s19
	s_addc_u32 s17, s7, 0
	global_load_dwordx4 v[202:205], v219, s[16:17]
	s_add_i32 m0, s58, 0xc000
	s_nop 0
	global_load_lds_dwordx4 v222, s[14:15]
	s_nop 7
	v_lshrrev_b32_e32 v249, v229, v198
	v_lshrrev_b32_e32 v250, v229, v199
	v_bfe_i32 v235, v249, 0, 1
	v_bfe_i32 v236, v250, 0, 1
	v_bfe_i32 v237, v249, 1, 1
	v_bfe_i32 v238, v250, 1, 1
	v_bfe_i32 v239, v249, 2, 1
	v_bfe_i32 v240, v250, 2, 1
	v_bfe_i32 v241, v249, 3, 1
	v_bfe_i32 v242, v250, 3, 1
	v_bitop3_b32 v34, v34, s33, v235 bitop3:0xe4
	v_bitop3_b32 v50, v50, s33, v236 bitop3:0xe4
	v_bitop3_b32 v35, v35, s33, v237 bitop3:0xe4
	v_bitop3_b32 v51, v51, s33, v238 bitop3:0xe4
	v_bitop3_b32 v36, v36, s33, v239 bitop3:0xe4
	v_bitop3_b32 v52, v52, s33, v240 bitop3:0xe4
	v_bitop3_b32 v37, v37, s33, v241 bitop3:0xe4
	v_bitop3_b32 v53, v53, s33, v242 bitop3:0xe4
	v_max3_f32 v247, v34, s33, v50
	v_max3_f32 v248, v35, s33, v51
	v_max3_f32 v247, v247, v36, v52
	v_max3_f32 v248, v248, v37, v53
	v_bfe_i32 v235, v249, 8, 1
	v_bfe_i32 v236, v250, 8, 1
	v_bfe_i32 v237, v249, 9, 1
	v_bfe_i32 v238, v250, 9, 1
	v_bfe_i32 v239, v249, 10, 1
	v_bfe_i32 v240, v250, 10, 1
	v_bfe_i32 v241, v249, 11, 1
	v_bfe_i32 v242, v250, 11, 1
	v_bitop3_b32 v38, v38, s33, v235 bitop3:0xe4
	v_bitop3_b32 v54, v54, s33, v236 bitop3:0xe4
	v_bitop3_b32 v39, v39, s33, v237 bitop3:0xe4
	v_bitop3_b32 v55, v55, s33, v238 bitop3:0xe4
	v_bitop3_b32 v40, v40, s33, v239 bitop3:0xe4
	v_bitop3_b32 v56, v56, s33, v240 bitop3:0xe4
	v_bitop3_b32 v41, v41, s33, v241 bitop3:0xe4
	v_bitop3_b32 v57, v57, s33, v242 bitop3:0xe4
	v_max3_f32 v247, v247, v38, v54
	v_max3_f32 v248, v248, v39, v55
	v_max3_f32 v247, v247, v40, v56
	v_max3_f32 v248, v248, v41, v57
	v_bfe_i32 v235, v249, 16, 1
	v_bfe_i32 v236, v250, 16, 1
	v_bfe_i32 v237, v249, 17, 1
	v_bfe_i32 v238, v250, 17, 1
	v_bfe_i32 v239, v249, 18, 1
	v_bfe_i32 v240, v250, 18, 1
	v_bfe_i32 v241, v249, 19, 1
	v_bfe_i32 v242, v250, 19, 1
	v_bitop3_b32 v42, v42, s33, v235 bitop3:0xe4
	v_bitop3_b32 v58, v58, s33, v236 bitop3:0xe4
	v_bitop3_b32 v43, v43, s33, v237 bitop3:0xe4
	v_bitop3_b32 v59, v59, s33, v238 bitop3:0xe4
	v_bitop3_b32 v44, v44, s33, v239 bitop3:0xe4
	v_bitop3_b32 v60, v60, s33, v240 bitop3:0xe4
	v_bitop3_b32 v45, v45, s33, v241 bitop3:0xe4
	v_bitop3_b32 v61, v61, s33, v242 bitop3:0xe4
	v_max3_f32 v247, v247, v42, v58
	v_max3_f32 v248, v248, v43, v59
	v_max3_f32 v247, v247, v44, v60
	v_max3_f32 v248, v248, v45, v61
	v_bfe_i32 v235, v249, 24, 1
	v_bfe_i32 v236, v250, 24, 1
	v_bfe_i32 v237, v249, 25, 1
	v_bfe_i32 v238, v250, 25, 1
	v_bfe_i32 v239, v249, 26, 1
	v_bfe_i32 v240, v250, 26, 1
	v_bfe_i32 v241, v249, 27, 1
	v_bfe_i32 v242, v250, 27, 1
	v_bitop3_b32 v46, v46, s33, v235 bitop3:0xe4
	v_bitop3_b32 v62, v62, s33, v236 bitop3:0xe4
	v_bitop3_b32 v47, v47, s33, v237 bitop3:0xe4
	v_bitop3_b32 v63, v63, s33, v238 bitop3:0xe4
	v_bitop3_b32 v48, v48, s33, v239 bitop3:0xe4
	v_bitop3_b32 v64, v64, s33, v240 bitop3:0xe4
	v_bitop3_b32 v49, v49, s33, v241 bitop3:0xe4
	v_bitop3_b32 v65, v65, s33, v242 bitop3:0xe4
	v_max3_f32 v247, v247, v46, v62
	v_max3_f32 v248, v248, v47, v63
	v_max3_f32 v247, v247, v48, v64
	v_max3_f32 v248, v248, v49, v65
	v_max_f32_e32 v247, v247, v248
	v_mov_b32_e32 v248, v247
	s_nop 1
	v_permlane32_swap_b32_e32 v247, v248
	v_max3_f32 v247, v230, v247, v248
	v_cmp_neq_f32_e32 vcc, s33, v247
	s_nop 1
	v_cndmask_b32_e32 v248, 0, v247, vcc
	v_sub_f32_e32 v33, v230, v248
	v_mul_f32_e32 v33, 0x3e38aa3b, v33
	v_exp_f32_e32 v232, v33
	v_mul_f32_e32 v234, 0xbe38aa3b, v248
	v_mov_b32_e32 v230, v247
.Lat_loop_0:
	s_add_i32 m0, s58, 0x0
	s_nop 0
	global_load_lds_dwordx4 v221, s[12:13]
	s_cmp_lt_u32 s8, s10
	s_cbranch_scc1 .Lat_full_0
	s_cmp_eq_u32 s8, s10
	s_cbranch_scc1 .Lat_last_0
.Lat_idle_0:
	s_add_u32 s8, s8, 1
	s_add_u32 s18, s8, 4
	s_min_u32 s18, s18, s11
	s_mul_i32 s18, s18, 0xb2c00
	s_add_u32 s12, s4, s18
	s_addc_u32 s13, s5, 0
	s_add_u32 s19, s8, 2
	s_min_u32 s19, s19, s11
	s_mul_i32 s18, s19, 0xb2c00
	s_add_u32 s14, s4, s18
	s_addc_u32 s15, s5, 0
	s_add_i32 m0, s58, 0xe000
	s_nop 0
	global_load_lds_dwordx4 v222, s[14:15]
	s_cmp_lt_u32 s8, s9
	s_waitcnt vmcnt(4)
	s_barrier
	s_cbranch_scc1 .Lat_loop_1
	s_branch .Lat_epilogue

.Lat_nors_f0:
	v_fmamk_f32 v34, v34, 0x3e38aa3b, v234
	v_fmamk_f32 v35, v35, 0x3e38aa3b, v234
	s_waitcnt lgkmcnt(7)
	v_mfma_f32_32x32x16_bf16 v[70:85], v[118:121], v[102:105], 0
	ds_read_b64_tr_b16 v[154:155], v227 offset:0
	ds_read_b64_tr_b16 v[156:157], v227 offset:1024
	v_fmamk_f32 v36, v36, 0x3e38aa3b, v234
	v_fmamk_f32 v37, v37, 0x3e38aa3b, v234
	v_fmamk_f32 v38, v38, 0x3e38aa3b, v234
	v_fmamk_f32 v39, v39, 0x3e38aa3b, v234
	v_fmamk_f32 v40, v40, 0x3e38aa3b, v234
	v_fmamk_f32 v41, v41, 0x3e38aa3b, v234
	v_exp_f32_e32 v34, v34
	v_exp_f32_e32 v35, v35
	v_exp_f32_e32 v36, v36
	v_exp_f32_e32 v37, v37
	v_exp_f32_e32 v38, v38
	v_exp_f32_e32 v39, v39
	s_waitcnt lgkmcnt(8)
	v_mfma_f32_32x32x16_bf16 v[86:101], v[122:125], v[102:105], 0
	ds_read_b64_tr_b16 v[158:159], v228 offset:0
	ds_read_b64_tr_b16 v[160:161], v228 offset:1024
	v_exp_f32_e32 v40, v40
	v_exp_f32_e32 v41, v41
	v_add_f32_e32 v243, v34, v38
	v_add_f32_e32 v244, v35, v39
	v_add_f32_e32 v245, v36, v40
	v_add_f32_e32 v246, v37, v41
	v_cvt_pk_bf16_f32 v34, v34, v35
	v_cvt_pk_bf16_f32 v35, v36, v37
	v_cvt_pk_bf16_f32 v36, v38, v39
	v_cvt_pk_bf16_f32 v37, v40, v41
	v_fmamk_f32 v42, v42, 0x3e38aa3b, v234
	v_fmamk_f32 v43, v43, 0x3e38aa3b, v234
	s_waitcnt lgkmcnt(9)
	v_mfma_f32_32x32x16_bf16 v[70:85], v[126:129], v[106:109], v[70:85]
	ds_read_b64_tr_b16 v[162:163], v227 offset:2048
	ds_read_b64_tr_b16 v[164:165], v227 offset:3072
	v_fmamk_f32 v44, v44, 0x3e38aa3b, v234
	v_fmamk_f32 v45, v45, 0x3e38aa3b, v234
	v_fmamk_f32 v46, v46, 0x3e38aa3b, v234
	v_fmamk_f32 v47, v47, 0x3e38aa3b, v234
	v_fmamk_f32 v48, v48, 0x3e38aa3b, v234
	v_fmamk_f32 v49, v49, 0x3e38aa3b, v234
	v_exp_f32_e32 v42, v42
	v_exp_f32_e32 v43, v43
	v_exp_f32_e32 v44, v44
	v_exp_f32_e32 v45, v45
	v_exp_f32_e32 v46, v46
	v_exp_f32_e32 v47, v47
	s_waitcnt lgkmcnt(10)
	v_mfma_f32_32x32x16_bf16 v[86:101], v[130:133], v[106:109], v[86:101]
	ds_read_b64_tr_b16 v[166:167], v228 offset:2048
	ds_read_b64_tr_b16 v[168:169], v228 offset:3072
	v_exp_f32_e32 v48, v48
	v_exp_f32_e32 v49, v49
	v_add_f32_e32 v243, v243, v42
	v_add_f32_e32 v244, v244, v43
	v_add_f32_e32 v245, v245, v44
	v_add_f32_e32 v246, v246, v45
	v_add_f32_e32 v243, v243, v46
	v_add_f32_e32 v244, v244, v47
	v_add_f32_e32 v245, v245, v48
	v_add_f32_e32 v246, v246, v49
	v_cvt_pk_bf16_f32 v42, v42, v43
	v_cvt_pk_bf16_f32 v43, v44, v45
	s_waitcnt lgkmcnt(11)
	v_mfma_f32_32x32x16_bf16 v[70:85], v[134:137], v[110:113], v[70:85]
	ds_read_b64_tr_b16 v[170:171], v227 offset:4096
	ds_read_b64_tr_b16 v[172:173], v227 offset:5120
	v_cvt_pk_bf16_f32 v44, v46, v47
	v_cvt_pk_bf16_f32 v45, v48, v49
	v_fmamk_f32 v50, v50, 0x3e38aa3b, v234
	v_fmamk_f32 v51, v51, 0x3e38aa3b, v234
	v_fmamk_f32 v52, v52, 0x3e38aa3b, v234
	v_fmamk_f32 v53, v53, 0x3e38aa3b, v234
	v_fmamk_f32 v54, v54, 0x3e38aa3b, v234
	v_fmamk_f32 v55, v55, 0x3e38aa3b, v234
	v_fmamk_f32 v56, v56, 0x3e38aa3b, v234
	v_fmamk_f32 v57, v57, 0x3e38aa3b, v234
	v_exp_f32_e32 v50, v50
	v_exp_f32_e32 v51, v51
	s_waitcnt lgkmcnt(12)
	v_mfma_f32_32x32x16_bf16 v[86:101], v[138:141], v[110:113], v[86:101]
	ds_read_b64_tr_b16 v[174:175], v228 offset:4096
	ds_read_b64_tr_b16 v[176:177], v228 offset:5120
	v_exp_f32_e32 v52, v52
	v_exp_f32_e32 v53, v53
	v_exp_f32_e32 v54, v54
	v_exp_f32_e32 v55, v55
	v_exp_f32_e32 v56, v56
	v_exp_f32_e32 v57, v57
	v_add_f32_e32 v243, v243, v50
	v_add_f32_e32 v244, v244, v51
	v_add_f32_e32 v245, v245, v52
	v_add_f32_e32 v246, v246, v53
	v_add_f32_e32 v243, v243, v54
	v_add_f32_e32 v244, v244, v55
	s_waitcnt lgkmcnt(13)
	v_mfma_f32_32x32x16_bf16 v[70:85], v[142:145], v[114:117], v[70:85]
	ds_read_b64_tr_b16 v[178:179], v227 offset:6144
	ds_read_b64_tr_b16 v[180:181], v227 offset:7168
	v_add_f32_e32 v245, v245, v56
	v_add_f32_e32 v246, v246, v57
	v_cvt_pk_bf16_f32 v50, v50, v51
	v_cvt_pk_bf16_f32 v51, v52, v53
	v_cvt_pk_bf16_f32 v52, v54, v55
	v_cvt_pk_bf16_f32 v53, v56, v57
	v_fmamk_f32 v58, v58, 0x3e38aa3b, v234
	v_fmamk_f32 v59, v59, 0x3e38aa3b, v234
	v_fmamk_f32 v60, v60, 0x3e38aa3b, v234
	v_fmamk_f32 v61, v61, 0x3e38aa3b, v234
	v_fmamk_f32 v62, v62, 0x3e38aa3b, v234
	v_fmamk_f32 v63, v63, 0x3e38aa3b, v234
	s_waitcnt lgkmcnt(14)
	v_mfma_f32_32x32x16_bf16 v[86:101], v[146:149], v[114:117], v[86:101]
	ds_read_b64_tr_b16 v[182:183], v228 offset:6144
	ds_read_b64_tr_b16 v[184:185], v228 offset:7168
	s_waitcnt lgkmcnt(14)
	v_fmamk_f32 v64, v64, 0x3e38aa3b, v234
	v_fmamk_f32 v65, v65, 0x3e38aa3b, v234
	v_exp_f32_e32 v58, v58
	v_exp_f32_e32 v59, v59
	v_exp_f32_e32 v60, v60
	v_exp_f32_e32 v61, v61
	v_exp_f32_e32 v62, v62
	v_exp_f32_e32 v63, v63
	v_exp_f32_e32 v64, v64
	v_exp_f32_e32 v65, v65
	v_add_f32_e32 v243, v243, v58
	v_add_f32_e32 v244, v244, v59
	v_add_f32_e32 v245, v245, v60
	v_add_f32_e32 v246, v246, v61
	s_waitcnt lgkmcnt(14)
	v_mfma_f32_32x32x16_bf16 v[0:15], v[154:157], v[34:37], v[0:15]
	ds_read_b128 v[118:121], v223 offset:16384
	v_add_f32_e32 v243, v243, v62
	v_add_f32_e32 v244, v244, v63
	v_add_f32_e32 v245, v245, v64
	v_add_f32_e32 v246, v246, v65
	v_cvt_pk_bf16_f32 v58, v58, v59
	v_cvt_pk_bf16_f32 v59, v60, v61
	v_cvt_pk_bf16_f32 v60, v62, v63
	v_cvt_pk_bf16_f32 v61, v64, v65
	v_add_f32_e32 v243, v243, v244
	v_add_f32_e32 v245, v245, v246
	v_add_f32_e32 v243, v243, v245
	v_fma_f32 v231, v231, v232, v243
	s_waitcnt lgkmcnt(13)
	v_mfma_f32_32x32x16_bf16 v[16:31], v[158:161], v[34:37], v[16:31]
	ds_read_b128 v[122:125], v223 offset:20480
	v_lshrrev_b32_e32 v249, v229, v200
	v_lshrrev_b32_e32 v250, v229, v201
	v_bfe_i32 v235, v249, 0, 1
	v_bfe_i32 v236, v250, 0, 1
	v_bfe_i32 v237, v249, 1, 1
	v_bfe_i32 v238, v250, 1, 1
	v_bfe_i32 v239, v249, 2, 1
	v_bfe_i32 v240, v250, 2, 1
	v_bfe_i32 v241, v249, 3, 1
	v_bfe_i32 v242, v250, 3, 1
	v_bitop3_b32 v70, v70, s33, v235 bitop3:0xe4
	s_waitcnt lgkmcnt(12)
	v_mfma_f32_32x32x16_bf16 v[0:15], v[162:165], v[42:45], v[0:15]
	ds_read_b128 v[126:129], v224 offset:16384
	v_bitop3_b32 v86, v86, s33, v236 bitop3:0xe4
	v_bitop3_b32 v71, v71, s33, v237 bitop3:0xe4
	v_bitop3_b32 v87, v87, s33, v238 bitop3:0xe4
	v_bitop3_b32 v72, v72, s33, v239 bitop3:0xe4
	v_bitop3_b32 v88, v88, s33, v240 bitop3:0xe4
	v_bitop3_b32 v73, v73, s33, v241 bitop3:0xe4
	v_bitop3_b32 v89, v89, s33, v242 bitop3:0xe4
	v_max3_f32 v247, v70, s33, v86
	v_max3_f32 v248, v71, s33, v87
	v_max3_f32 v247, v247, v72, v88
	v_max3_f32 v248, v248, v73, v89
	v_bfe_i32 v235, v249, 8, 1
	s_waitcnt lgkmcnt(11)
	v_mfma_f32_32x32x16_bf16 v[16:31], v[166:169], v[42:45], v[16:31]
	ds_read_b128 v[130:133], v224 offset:20480
	v_bfe_i32 v236, v250, 8, 1
	v_bfe_i32 v237, v249, 9, 1
	v_bfe_i32 v238, v250, 9, 1
	v_bfe_i32 v239, v249, 10, 1
	v_bfe_i32 v240, v250, 10, 1
	v_bfe_i32 v241, v249, 11, 1
	v_bfe_i32 v242, v250, 11, 1
	v_bitop3_b32 v74, v74, s33, v235 bitop3:0xe4
	v_bitop3_b32 v90, v90, s33, v236 bitop3:0xe4
	v_bitop3_b32 v75, v75, s33, v237 bitop3:0xe4
	v_bitop3_b32 v91, v91, s33, v238 bitop3:0xe4
	v_bitop3_b32 v76, v76, s33, v239 bitop3:0xe4
	s_waitcnt lgkmcnt(10)
	v_mfma_f32_32x32x16_bf16 v[0:15], v[170:173], v[50:53], v[0:15]
	ds_read_b128 v[134:137], v225 offset:16384
	v_bitop3_b32 v92, v92, s33, v240 bitop3:0xe4
	v_bitop3_b32 v77, v77, s33, v241 bitop3:0xe4
	v_bitop3_b32 v93, v93, s33, v242 bitop3:0xe4
	v_max3_f32 v247, v247, v74, v90
	v_max3_f32 v248, v248, v75, v91
	v_max3_f32 v247, v247, v76, v92
	v_max3_f32 v248, v248, v77, v93
	v_bfe_i32 v235, v249, 16, 1
	v_bfe_i32 v236, v250, 16, 1
	v_bfe_i32 v237, v249, 17, 1
	v_bfe_i32 v238, v250, 17, 1
	v_bfe_i32 v239, v249, 18, 1
	s_waitcnt lgkmcnt(9)
	v_mfma_f32_32x32x16_bf16 v[16:31], v[174:177], v[50:53], v[16:31]
	ds_read_b128 v[138:141], v225 offset:20480
	v_bfe_i32 v240, v250, 18, 1
	v_bfe_i32 v241, v249, 19, 1
	v_bfe_i32 v242, v250, 19, 1
	v_bitop3_b32 v78, v78, s33, v235 bitop3:0xe4
	v_bitop3_b32 v94, v94, s33, v236 bitop3:0xe4
	v_bitop3_b32 v79, v79, s33, v237 bitop3:0xe4
	v_bitop3_b32 v95, v95, s33, v238 bitop3:0xe4
	v_bitop3_b32 v80, v80, s33, v239 bitop3:0xe4
	v_bitop3_b32 v96, v96, s33, v240 bitop3:0xe4
	v_bitop3_b32 v81, v81, s33, v241 bitop3:0xe4
	v_bitop3_b32 v97, v97, s33, v242 bitop3:0xe4
	v_max3_f32 v247, v247, v78, v94
	s_waitcnt lgkmcnt(8)
	v_mfma_f32_32x32x16_bf16 v[0:15], v[178:181], v[58:61], v[0:15]
	ds_read_b128 v[142:145], v226 offset:16384
	v_max3_f32 v248, v248, v79, v95
	v_max3_f32 v247, v247, v80, v96
	v_max3_f32 v248, v248, v81, v97
	v_bfe_i32 v235, v249, 24, 1
	v_bfe_i32 v236, v250, 24, 1
	v_bfe_i32 v237, v249, 25, 1
	v_bfe_i32 v238, v250, 25, 1
	v_bfe_i32 v239, v249, 26, 1
	v_bfe_i32 v240, v250, 26, 1
	v_bfe_i32 v241, v249, 27, 1
	v_bfe_i32 v242, v250, 27, 1
	v_bitop3_b32 v82, v82, s33, v235 bitop3:0xe4
	s_waitcnt lgkmcnt(7)
	v_mfma_f32_32x32x16_bf16 v[16:31], v[182:185], v[58:61], v[16:31]
	ds_read_b128 v[146:149], v226 offset:20480
	v_bitop3_b32 v98, v98, s33, v236 bitop3:0xe4
	v_bitop3_b32 v83, v83, s33, v237 bitop3:0xe4
	v_bitop3_b32 v99, v99, s33, v238 bitop3:0xe4
	v_bitop3_b32 v84, v84, s33, v239 bitop3:0xe4
	v_bitop3_b32 v100, v100, s33, v240 bitop3:0xe4
	v_bitop3_b32 v85, v85, s33, v241 bitop3:0xe4
	v_bitop3_b32 v101, v101, s33, v242 bitop3:0xe4
	v_max3_f32 v247, v247, v82, v98
	v_max3_f32 v248, v248, v83, v99
	v_max3_f32 v247, v247, v84, v100
	v_max3_f32 v248, v248, v85, v101
	v_max_f32_e32 v247, v247, v248
	v_mov_b32_e32 v248, v247
	s_nop 1
	v_permlane32_swap_b32_e32 v247, v248
	v_max3_f32 v247, v230, v247, v248
	v_cmp_neq_f32_e32 vcc, s33, v247
	s_nop 1
	v_cndmask_b32_e32 v248, 0, v247, vcc
	v_sub_f32_e32 v33, v230, v248
	v_mul_f32_e32 v33, 0x3e38aa3b, v33
	v_exp_f32_e32 v232, v33
	v_mul_f32_e32 v234, 0xbe38aa3b, v248
	v_mov_b32_e32 v230, v247
	s_add_u32 s8, s8, 1
	s_add_u32 s18, s8, 4
	s_min_u32 s18, s18, s11
	s_mul_i32 s18, s18, 0xb2c00
	s_add_u32 s12, s4, s18
	s_addc_u32 s13, s5, 0
	s_add_u32 s19, s8, 2
	s_min_u32 s19, s19, s11
	s_mul_i32 s18, s19, 0xb2c00
	s_add_u32 s14, s4, s18
	s_addc_u32 s15, s5, 0
	s_add_i32 m0, s58, 0xe000
	s_nop 0
	global_load_lds_dwordx4 v222, s[14:15]
	s_cmp_lt_u32 s8, s9
	s_waitcnt vmcnt(4)
	s_barrier
	s_cbranch_scc1 .Lat_loop_1
	s_branch .Lat_epilogue

.Lat_nors_l0:
	v_fmamk_f32 v34, v34, 0x3e38aa3b, v234
	v_fmamk_f32 v35, v35, 0x3e38aa3b, v234
	v_fmamk_f32 v36, v36, 0x3e38aa3b, v234
	ds_read_b64_tr_b16 v[168:169], v228 offset:3072
	s_waitcnt lgkmcnt(14)
	v_fmamk_f32 v37, v37, 0x3e38aa3b, v234
	v_fmamk_f32 v38, v38, 0x3e38aa3b, v234
	v_fmamk_f32 v39, v39, 0x3e38aa3b, v234
	ds_read_b64_tr_b16 v[170:171], v227 offset:4096
	s_waitcnt lgkmcnt(14)
	v_fmamk_f32 v40, v40, 0x3e38aa3b, v234
	v_fmamk_f32 v41, v41, 0x3e38aa3b, v234
	v_exp_f32_e32 v34, v34
	ds_read_b64_tr_b16 v[172:173], v227 offset:5120
	s_waitcnt lgkmcnt(14)
	v_exp_f32_e32 v35, v35
	v_exp_f32_e32 v36, v36
	v_exp_f32_e32 v37, v37
	ds_read_b64_tr_b16 v[174:175], v228 offset:4096
	s_waitcnt lgkmcnt(14)
	v_exp_f32_e32 v38, v38
	v_exp_f32_e32 v39, v39
	v_exp_f32_e32 v40, v40
	ds_read_b64_tr_b16 v[176:177], v228 offset:5120
	s_waitcnt lgkmcnt(14)
	v_exp_f32_e32 v41, v41
	v_add_f32_e32 v243, v34, v38
	v_add_f32_e32 v244, v35, v39
	ds_read_b64_tr_b16 v[178:179], v227 offset:6144
	s_waitcnt lgkmcnt(14)
	v_add_f32_e32 v245, v36, v40
	v_add_f32_e32 v246, v37, v41
	v_cvt_pk_bf16_f32 v34, v34, v35
	ds_read_b64_tr_b16 v[180:181], v227 offset:7168
	s_waitcnt lgkmcnt(14)
	v_cvt_pk_bf16_f32 v35, v36, v37
	v_cvt_pk_bf16_f32 v36, v38, v39
	v_cvt_pk_bf16_f32 v37, v40, v41
	ds_read_b64_tr_b16 v[182:183], v228 offset:6144
	s_waitcnt lgkmcnt(14)
	s_waitcnt lgkmcnt(13)
	v_mfma_f32_32x32x16_bf16 v[0:15], v[154:157], v[34:37], v[0:15]
	s_waitcnt lgkmcnt(11)
	v_mfma_f32_32x32x16_bf16 v[16:31], v[158:161], v[34:37], v[16:31]
	v_fmamk_f32 v42, v42, 0x3e38aa3b, v234
	v_fmamk_f32 v43, v43, 0x3e38aa3b, v234
	v_fmamk_f32 v44, v44, 0x3e38aa3b, v234
	ds_read_b64_tr_b16 v[184:185], v228 offset:7168
	v_fmamk_f32 v45, v45, 0x3e38aa3b, v234
	v_fmamk_f32 v46, v46, 0x3e38aa3b, v234
	v_fmamk_f32 v47, v47, 0x3e38aa3b, v234
	v_fmamk_f32 v48, v48, 0x3e38aa3b, v234
	v_fmamk_f32 v49, v49, 0x3e38aa3b, v234
	v_exp_f32_e32 v42, v42
	v_exp_f32_e32 v43, v43
	v_exp_f32_e32 v44, v44
	v_exp_f32_e32 v45, v45
	v_exp_f32_e32 v46, v46
	v_exp_f32_e32 v47, v47
	v_exp_f32_e32 v48, v48
	v_exp_f32_e32 v49, v49
	v_add_f32_e32 v243, v243, v42
	v_add_f32_e32 v244, v244, v43
	v_add_f32_e32 v245, v245, v44
	v_add_f32_e32 v246, v246, v45
	v_add_f32_e32 v243, v243, v46
	v_add_f32_e32 v244, v244, v47
	v_add_f32_e32 v245, v245, v48
	v_add_f32_e32 v246, v246, v49
	v_cvt_pk_bf16_f32 v42, v42, v43
	v_cvt_pk_bf16_f32 v43, v44, v45
	v_cvt_pk_bf16_f32 v44, v46, v47
	v_cvt_pk_bf16_f32 v45, v48, v49
	s_waitcnt lgkmcnt(10)
	v_mfma_f32_32x32x16_bf16 v[0:15], v[162:165], v[42:45], v[0:15]
	s_waitcnt lgkmcnt(8)
	v_mfma_f32_32x32x16_bf16 v[16:31], v[166:169], v[42:45], v[16:31]
	v_fmamk_f32 v50, v50, 0x3e38aa3b, v234
	v_fmamk_f32 v51, v51, 0x3e38aa3b, v234
	v_fmamk_f32 v52, v52, 0x3e38aa3b, v234
	v_fmamk_f32 v53, v53, 0x3e38aa3b, v234
	v_fmamk_f32 v54, v54, 0x3e38aa3b, v234
	v_fmamk_f32 v55, v55, 0x3e38aa3b, v234
	v_fmamk_f32 v56, v56, 0x3e38aa3b, v234
	v_fmamk_f32 v57, v57, 0x3e38aa3b, v234
	v_exp_f32_e32 v50, v50
	v_exp_f32_e32 v51, v51
	v_exp_f32_e32 v52, v52
	v_exp_f32_e32 v53, v53
	v_exp_f32_e32 v54, v54
	v_exp_f32_e32 v55, v55
	v_exp_f32_e32 v56, v56
	v_exp_f32_e32 v57, v57
	v_add_f32_e32 v243, v243, v50
	v_add_f32_e32 v244, v244, v51
	v_add_f32_e32 v245, v245, v52
	v_add_f32_e32 v246, v246, v53
	v_add_f32_e32 v243, v243, v54
	v_add_f32_e32 v244, v244, v55
	v_add_f32_e32 v245, v245, v56
	v_add_f32_e32 v246, v246, v57
	v_cvt_pk_bf16_f32 v50, v50, v51
	v_cvt_pk_bf16_f32 v51, v52, v53
	v_cvt_pk_bf16_f32 v52, v54, v55
	v_cvt_pk_bf16_f32 v53, v56, v57
	s_waitcnt lgkmcnt(6)
	v_mfma_f32_32x32x16_bf16 v[0:15], v[170:173], v[50:53], v[0:15]
	s_waitcnt lgkmcnt(4)
	v_mfma_f32_32x32x16_bf16 v[16:31], v[174:177], v[50:53], v[16:31]
	v_fmamk_f32 v58, v58, 0x3e38aa3b, v234
	v_fmamk_f32 v59, v59, 0x3e38aa3b, v234
	v_fmamk_f32 v60, v60, 0x3e38aa3b, v234
	v_fmamk_f32 v61, v61, 0x3e38aa3b, v234
	v_fmamk_f32 v62, v62, 0x3e38aa3b, v234
	v_fmamk_f32 v63, v63, 0x3e38aa3b, v234
	v_fmamk_f32 v64, v64, 0x3e38aa3b, v234
	v_fmamk_f32 v65, v65, 0x3e38aa3b, v234
	v_exp_f32_e32 v58, v58
	v_exp_f32_e32 v59, v59
	v_exp_f32_e32 v60, v60
	v_exp_f32_e32 v61, v61
	v_exp_f32_e32 v62, v62
	v_exp_f32_e32 v63, v63
	v_exp_f32_e32 v64, v64
	v_exp_f32_e32 v65, v65
	v_add_f32_e32 v243, v243, v58
	v_add_f32_e32 v244, v244, v59
	v_add_f32_e32 v245, v245, v60
	v_add_f32_e32 v246, v246, v61
	v_add_f32_e32 v243, v243, v62
	v_add_f32_e32 v244, v244, v63
	v_add_f32_e32 v245, v245, v64
	v_add_f32_e32 v246, v246, v65
	v_cvt_pk_bf16_f32 v58, v58, v59
	v_cvt_pk_bf16_f32 v59, v60, v61
	v_cvt_pk_bf16_f32 v60, v62, v63
	v_cvt_pk_bf16_f32 v61, v64, v65
	v_add_f32_e32 v243, v243, v244
	v_add_f32_e32 v245, v245, v246
	v_add_f32_e32 v243, v243, v245
	v_fma_f32 v231, v231, v232, v243
	s_waitcnt lgkmcnt(2)
	v_mfma_f32_32x32x16_bf16 v[0:15], v[178:181], v[58:61], v[0:15]
	s_waitcnt lgkmcnt(0)
	v_mfma_f32_32x32x16_bf16 v[16:31], v[182:185], v[58:61], v[16:31]
	s_add_u32 s8, s8, 1
	s_add_u32 s18, s8, 4
	s_min_u32 s18, s18, s11
	s_mul_i32 s18, s18, 0xb2c00
	s_add_u32 s12, s4, s18
	s_addc_u32 s13, s5, 0
	s_add_u32 s19, s8, 2
	s_min_u32 s19, s19, s11
	s_mul_i32 s18, s19, 0xb2c00
	s_add_u32 s14, s4, s18
	s_addc_u32 s15, s5, 0
	s_add_i32 m0, s58, 0xe000
	s_nop 0
	global_load_lds_dwordx4 v222, s[14:15]
	s_cmp_lt_u32 s8, s9
	s_waitcnt vmcnt(4)
	s_barrier
	s_cbranch_scc1 .Lat_loop_1
	s_branch .Lat_epilogue
.Lat_loop_1:
	s_add_i32 m0, s58, 0x2000
	s_nop 0
	global_load_lds_dwordx4 v221, s[12:13]
	s_cmp_lt_u32 s8, s10
	s_cbranch_scc1 .Lat_full_1
	s_cmp_eq_u32 s8, s10
	s_cbranch_scc1 .Lat_last_1
.Lat_idle_1:
	s_add_u32 s8, s8, 1
	s_add_u32 s18, s8, 4
	s_min_u32 s18, s18, s11
	s_mul_i32 s18, s18, 0xb2c00
	s_add_u32 s12, s4, s18
	s_addc_u32 s13, s5, 0
	s_add_u32 s19, s8, 2
	s_min_u32 s19, s19, s11
	s_mul_i32 s18, s19, 0xb2c00
	s_add_u32 s14, s4, s18
	s_addc_u32 s15, s5, 0
	s_lshl_b32 s19, s19, 3
	s_add_u32 s16, s6, s19
	s_addc_u32 s17, s7, 0
	global_load_dwordx4 v[198:201], v219, s[16:17]
	s_add_i32 m0, s58, 0x8000
	s_nop 0
	global_load_lds_dwordx4 v222, s[14:15]
	s_cmp_lt_u32 s8, s9
	s_waitcnt vmcnt(4)
	s_barrier
	s_cbranch_scc1 .Lat_loop_2
	s_branch .Lat_epilogue

.Lat_nors_f1:
	v_fmamk_f32 v70, v70, 0x3e38aa3b, v234
	v_fmamk_f32 v71, v71, 0x3e38aa3b, v234
	s_waitcnt lgkmcnt(7)
	v_mfma_f32_32x32x16_bf16 v[34:49], v[118:121], v[102:105], 0
	ds_read_b64_tr_b16 v[154:155], v227 offset:8192
	ds_read_b64_tr_b16 v[156:157], v227 offset:9216
	v_fmamk_f32 v72, v72, 0x3e38aa3b, v234
	v_fmamk_f32 v73, v73, 0x3e38aa3b, v234
	v_fmamk_f32 v74, v74, 0x3e38aa3b, v234
	v_fmamk_f32 v75, v75, 0x3e38aa3b, v234
	v_fmamk_f32 v76, v76, 0x3e38aa3b, v234
	v_fmamk_f32 v77, v77, 0x3e38aa3b, v234
	v_exp_f32_e32 v70, v70
	v_exp_f32_e32 v71, v71
	v_exp_f32_e32 v72, v72
	v_exp_f32_e32 v73, v73
	v_exp_f32_e32 v74, v74
	v_exp_f32_e32 v75, v75
	s_waitcnt lgkmcnt(8)
	v_mfma_f32_32x32x16_bf16 v[50:65], v[122:125], v[102:105], 0
	ds_read_b64_tr_b16 v[158:159], v228 offset:8192
	ds_read_b64_tr_b16 v[160:161], v228 offset:9216
	v_exp_f32_e32 v76, v76
	v_exp_f32_e32 v77, v77
	v_add_f32_e32 v243, v70, v74
	v_add_f32_e32 v244, v71, v75
	v_add_f32_e32 v245, v72, v76
	v_add_f32_e32 v246, v73, v77
	v_cvt_pk_bf16_f32 v70, v70, v71
	v_cvt_pk_bf16_f32 v71, v72, v73
	v_cvt_pk_bf16_f32 v72, v74, v75
	v_cvt_pk_bf16_f32 v73, v76, v77
	v_fmamk_f32 v78, v78, 0x3e38aa3b, v234
	v_fmamk_f32 v79, v79, 0x3e38aa3b, v234
	s_waitcnt lgkmcnt(9)
	v_mfma_f32_32x32x16_bf16 v[34:49], v[126:129], v[106:109], v[34:49]
	ds_read_b64_tr_b16 v[162:163], v227 offset:10240
	ds_read_b64_tr_b16 v[164:165], v227 offset:11264
	v_fmamk_f32 v80, v80, 0x3e38aa3b, v234
	v_fmamk_f32 v81, v81, 0x3e38aa3b, v234
	v_fmamk_f32 v82, v82, 0x3e38aa3b, v234
	v_fmamk_f32 v83, v83, 0x3e38aa3b, v234
	v_fmamk_f32 v84, v84, 0x3e38aa3b, v234
	v_fmamk_f32 v85, v85, 0x3e38aa3b, v234
	v_exp_f32_e32 v78, v78
	v_exp_f32_e32 v79, v79
	v_exp_f32_e32 v80, v80
	v_exp_f32_e32 v81, v81
	v_exp_f32_e32 v82, v82
	v_exp_f32_e32 v83, v83
	s_waitcnt lgkmcnt(10)
	v_mfma_f32_32x32x16_bf16 v[50:65], v[130:133], v[106:109], v[50:65]
	ds_read_b64_tr_b16 v[166:167], v228 offset:10240
	ds_read_b64_tr_b16 v[168:169], v228 offset:11264
	v_exp_f32_e32 v84, v84
	v_exp_f32_e32 v85, v85
	v_add_f32_e32 v243, v243, v78
	v_add_f32_e32 v244, v244, v79
	v_add_f32_e32 v245, v245, v80
	v_add_f32_e32 v246, v246, v81
	v_add_f32_e32 v243, v243, v82
	v_add_f32_e32 v244, v244, v83
	v_add_f32_e32 v245, v245, v84
	v_add_f32_e32 v246, v246, v85
	v_cvt_pk_bf16_f32 v78, v78, v79
	v_cvt_pk_bf16_f32 v79, v80, v81
	s_waitcnt lgkmcnt(11)
	v_mfma_f32_32x32x16_bf16 v[34:49], v[134:137], v[110:113], v[34:49]
	ds_read_b64_tr_b16 v[170:171], v227 offset:12288
	ds_read_b64_tr_b16 v[172:173], v227 offset:13312
	v_cvt_pk_bf16_f32 v80, v82, v83
	v_cvt_pk_bf16_f32 v81, v84, v85
	v_fmamk_f32 v86, v86, 0x3e38aa3b, v234
	v_fmamk_f32 v87, v87, 0x3e38aa3b, v234
	v_fmamk_f32 v88, v88, 0x3e38aa3b, v234
	v_fmamk_f32 v89, v89, 0x3e38aa3b, v234
	v_fmamk_f32 v90, v90, 0x3e38aa3b, v234
	v_fmamk_f32 v91, v91, 0x3e38aa3b, v234
	v_fmamk_f32 v92, v92, 0x3e38aa3b, v234
	v_fmamk_f32 v93, v93, 0x3e38aa3b, v234
	v_exp_f32_e32 v86, v86
	v_exp_f32_e32 v87, v87
	s_waitcnt lgkmcnt(12)
	v_mfma_f32_32x32x16_bf16 v[50:65], v[138:141], v[110:113], v[50:65]
	ds_read_b64_tr_b16 v[174:175], v228 offset:12288
	ds_read_b64_tr_b16 v[176:177], v228 offset:13312
	v_exp_f32_e32 v88, v88
	v_exp_f32_e32 v89, v89
	v_exp_f32_e32 v90, v90
	v_exp_f32_e32 v91, v91
	v_exp_f32_e32 v92, v92
	v_exp_f32_e32 v93, v93
	v_add_f32_e32 v243, v243, v86
	v_add_f32_e32 v244, v244, v87
	v_add_f32_e32 v245, v245, v88
	v_add_f32_e32 v246, v246, v89
	v_add_f32_e32 v243, v243, v90
	v_add_f32_e32 v244, v244, v91
	s_waitcnt lgkmcnt(13)
	v_mfma_f32_32x32x16_bf16 v[34:49], v[142:145], v[114:117], v[34:49]
	ds_read_b64_tr_b16 v[178:179], v227 offset:14336
	ds_read_b64_tr_b16 v[180:181], v227 offset:15360
	v_add_f32_e32 v245, v245, v92
	v_add_f32_e32 v246, v246, v93
	v_cvt_pk_bf16_f32 v86, v86, v87
	v_cvt_pk_bf16_f32 v87, v88, v89
	v_cvt_pk_bf16_f32 v88, v90, v91
	v_cvt_pk_bf16_f32 v89, v92, v93
	v_fmamk_f32 v94, v94, 0x3e38aa3b, v234
	v_fmamk_f32 v95, v95, 0x3e38aa3b, v234
	v_fmamk_f32 v96, v96, 0x3e38aa3b, v234
	v_fmamk_f32 v97, v97, 0x3e38aa3b, v234
	v_fmamk_f32 v98, v98, 0x3e38aa3b, v234
	v_fmamk_f32 v99, v99, 0x3e38aa3b, v234
	s_waitcnt lgkmcnt(14)
	v_mfma_f32_32x32x16_bf16 v[50:65], v[146:149], v[114:117], v[50:65]
	ds_read_b64_tr_b16 v[182:183], v228 offset:14336
	ds_read_b64_tr_b16 v[184:185], v228 offset:15360
	s_waitcnt lgkmcnt(14)
	v_fmamk_f32 v100, v100, 0x3e38aa3b, v234
	v_fmamk_f32 v101, v101, 0x3e38aa3b, v234
	v_exp_f32_e32 v94, v94
	v_exp_f32_e32 v95, v95
	v_exp_f32_e32 v96, v96
	v_exp_f32_e32 v97, v97
	v_exp_f32_e32 v98, v98
	v_exp_f32_e32 v99, v99
	v_exp_f32_e32 v100, v100
	v_exp_f32_e32 v101, v101
	v_add_f32_e32 v243, v243, v94
	v_add_f32_e32 v244, v244, v95
	v_add_f32_e32 v245, v245, v96
	v_add_f32_e32 v246, v246, v97
	s_waitcnt lgkmcnt(14)
	v_mfma_f32_32x32x16_bf16 v[0:15], v[154:157], v[70:73], v[0:15]
	ds_read_b128 v[118:121], v223 offset:24576
	v_add_f32_e32 v243, v243, v98
	v_add_f32_e32 v244, v244, v99
	v_add_f32_e32 v245, v245, v100
	v_add_f32_e32 v246, v246, v101
	v_cvt_pk_bf16_f32 v94, v94, v95
	v_cvt_pk_bf16_f32 v95, v96, v97
	v_cvt_pk_bf16_f32 v96, v98, v99
	v_cvt_pk_bf16_f32 v97, v100, v101
	v_add_f32_e32 v243, v243, v244
	v_add_f32_e32 v245, v245, v246
	v_add_f32_e32 v243, v243, v245
	v_fma_f32 v231, v231, v232, v243
	s_waitcnt lgkmcnt(13)
	v_mfma_f32_32x32x16_bf16 v[16:31], v[158:161], v[70:73], v[16:31]
	ds_read_b128 v[122:125], v223 offset:28672
	s_waitcnt vmcnt(4)
	v_lshrrev_b32_e32 v249, v229, v202
	v_lshrrev_b32_e32 v250, v229, v203
	v_bfe_i32 v235, v249, 0, 1
	v_bfe_i32 v236, v250, 0, 1
	v_bfe_i32 v237, v249, 1, 1
	v_bfe_i32 v238, v250, 1, 1
	v_bfe_i32 v239, v249, 2, 1
	v_bfe_i32 v240, v250, 2, 1
	v_bfe_i32 v241, v249, 3, 1
	v_bfe_i32 v242, v250, 3, 1
	v_bitop3_b32 v34, v34, s33, v235 bitop3:0xe4
	s_waitcnt lgkmcnt(12)
	v_mfma_f32_32x32x16_bf16 v[0:15], v[162:165], v[78:81], v[0:15]
	ds_read_b128 v[126:129], v224 offset:24576
	v_bitop3_b32 v50, v50, s33, v236 bitop3:0xe4
	v_bitop3_b32 v35, v35, s33, v237 bitop3:0xe4
	v_bitop3_b32 v51, v51, s33, v238 bitop3:0xe4
	v_bitop3_b32 v36, v36, s33, v239 bitop3:0xe4
	v_bitop3_b32 v52, v52, s33, v240 bitop3:0xe4
	v_bitop3_b32 v37, v37, s33, v241 bitop3:0xe4
	v_bitop3_b32 v53, v53, s33, v242 bitop3:0xe4
	v_max3_f32 v247, v34, s33, v50
	v_max3_f32 v248, v35, s33, v51
	v_max3_f32 v247, v247, v36, v52
	v_max3_f32 v248, v248, v37, v53
	v_bfe_i32 v235, v249, 8, 1
	s_waitcnt lgkmcnt(11)
	v_mfma_f32_32x32x16_bf16 v[16:31], v[166:169], v[78:81], v[16:31]
	ds_read_b128 v[130:133], v224 offset:28672
	v_bfe_i32 v236, v250, 8, 1
	v_bfe_i32 v237, v249, 9, 1
	v_bfe_i32 v238, v250, 9, 1
	v_bfe_i32 v239, v249, 10, 1
	v_bfe_i32 v240, v250, 10, 1
	v_bfe_i32 v241, v249, 11, 1
	v_bfe_i32 v242, v250, 11, 1
	v_bitop3_b32 v38, v38, s33, v235 bitop3:0xe4
	v_bitop3_b32 v54, v54, s33, v236 bitop3:0xe4
	v_bitop3_b32 v39, v39, s33, v237 bitop3:0xe4
	v_bitop3_b32 v55, v55, s33, v238 bitop3:0xe4
	v_bitop3_b32 v40, v40, s33, v239 bitop3:0xe4
	s_waitcnt lgkmcnt(10)
	v_mfma_f32_32x32x16_bf16 v[0:15], v[170:173], v[86:89], v[0:15]
	ds_read_b128 v[134:137], v225 offset:24576
	v_bitop3_b32 v56, v56, s33, v240 bitop3:0xe4
	v_bitop3_b32 v41, v41, s33, v241 bitop3:0xe4
	v_bitop3_b32 v57, v57, s33, v242 bitop3:0xe4
	v_max3_f32 v247, v247, v38, v54
	v_max3_f32 v248, v248, v39, v55
	v_max3_f32 v247, v247, v40, v56
	v_max3_f32 v248, v248, v41, v57
	v_bfe_i32 v235, v249, 16, 1
	v_bfe_i32 v236, v250, 16, 1
	v_bfe_i32 v237, v249, 17, 1
	v_bfe_i32 v238, v250, 17, 1
	v_bfe_i32 v239, v249, 18, 1
	s_waitcnt lgkmcnt(9)
	v_mfma_f32_32x32x16_bf16 v[16:31], v[174:177], v[86:89], v[16:31]
	ds_read_b128 v[138:141], v225 offset:28672
	v_bfe_i32 v240, v250, 18, 1
	v_bfe_i32 v241, v249, 19, 1
	v_bfe_i32 v242, v250, 19, 1
	v_bitop3_b32 v42, v42, s33, v235 bitop3:0xe4
	v_bitop3_b32 v58, v58, s33, v236 bitop3:0xe4
	v_bitop3_b32 v43, v43, s33, v237 bitop3:0xe4
	v_bitop3_b32 v59, v59, s33, v238 bitop3:0xe4
	v_bitop3_b32 v44, v44, s33, v239 bitop3:0xe4
	v_bitop3_b32 v60, v60, s33, v240 bitop3:0xe4
	v_bitop3_b32 v45, v45, s33, v241 bitop3:0xe4
	v_bitop3_b32 v61, v61, s33, v242 bitop3:0xe4
	v_max3_f32 v247, v247, v42, v58
	s_waitcnt lgkmcnt(8)
	v_mfma_f32_32x32x16_bf16 v[0:15], v[178:181], v[94:97], v[0:15]
	ds_read_b128 v[142:145], v226 offset:24576
	v_max3_f32 v248, v248, v43, v59
	v_max3_f32 v247, v247, v44, v60
	v_max3_f32 v248, v248, v45, v61
	v_bfe_i32 v235, v249, 24, 1
	v_bfe_i32 v236, v250, 24, 1
	v_bfe_i32 v237, v249, 25, 1
	v_bfe_i32 v238, v250, 25, 1
	v_bfe_i32 v239, v249, 26, 1
	v_bfe_i32 v240, v250, 26, 1
	v_bfe_i32 v241, v249, 27, 1
	v_bfe_i32 v242, v250, 27, 1
	v_bitop3_b32 v46, v46, s33, v235 bitop3:0xe4
	s_waitcnt lgkmcnt(7)
	v_mfma_f32_32x32x16_bf16 v[16:31], v[182:185], v[94:97], v[16:31]
	ds_read_b128 v[146:149], v226 offset:28672
	v_bitop3_b32 v62, v62, s33, v236 bitop3:0xe4
	v_bitop3_b32 v47, v47, s33, v237 bitop3:0xe4
	v_bitop3_b32 v63, v63, s33, v238 bitop3:0xe4
	v_bitop3_b32 v48, v48, s33, v239 bitop3:0xe4
	v_bitop3_b32 v64, v64, s33, v240 bitop3:0xe4
	v_bitop3_b32 v49, v49, s33, v241 bitop3:0xe4
	v_bitop3_b32 v65, v65, s33, v242 bitop3:0xe4
	v_max3_f32 v247, v247, v46, v62
	v_max3_f32 v248, v248, v47, v63
	v_max3_f32 v247, v247, v48, v64
	v_max3_f32 v248, v248, v49, v65
	v_max_f32_e32 v247, v247, v248
	v_mov_b32_e32 v248, v247
	s_nop 1
	v_permlane32_swap_b32_e32 v247, v248
	v_max3_f32 v247, v230, v247, v248
	v_cmp_neq_f32_e32 vcc, s33, v247
	s_nop 1
	v_cndmask_b32_e32 v248, 0, v247, vcc
	v_sub_f32_e32 v33, v230, v248
	v_mul_f32_e32 v33, 0x3e38aa3b, v33
	v_exp_f32_e32 v232, v33
	v_mul_f32_e32 v234, 0xbe38aa3b, v248
	v_mov_b32_e32 v230, v247
	s_add_u32 s8, s8, 1
	s_add_u32 s18, s8, 4
	s_min_u32 s18, s18, s11
	s_mul_i32 s18, s18, 0xb2c00
	s_add_u32 s12, s4, s18
	s_addc_u32 s13, s5, 0
	s_add_u32 s19, s8, 2
	s_min_u32 s19, s19, s11
	s_mul_i32 s18, s19, 0xb2c00
	s_add_u32 s14, s4, s18
	s_addc_u32 s15, s5, 0
	s_lshl_b32 s19, s19, 3
	s_add_u32 s16, s6, s19
	s_addc_u32 s17, s7, 0
	global_load_dwordx4 v[198:201], v219, s[16:17]
	s_add_i32 m0, s58, 0x8000
	s_nop 0
	global_load_lds_dwordx4 v222, s[14:15]
	s_cmp_lt_u32 s8, s9
	s_waitcnt vmcnt(4)
	s_barrier
	s_cbranch_scc1 .Lat_loop_2
	s_branch .Lat_epilogue

.Lat_nors_l1:
	v_fmamk_f32 v70, v70, 0x3e38aa3b, v234
	v_fmamk_f32 v71, v71, 0x3e38aa3b, v234
	v_fmamk_f32 v72, v72, 0x3e38aa3b, v234
	ds_read_b64_tr_b16 v[168:169], v228 offset:11264
	s_waitcnt lgkmcnt(14)
	v_fmamk_f32 v73, v73, 0x3e38aa3b, v234
	v_fmamk_f32 v74, v74, 0x3e38aa3b, v234
	v_fmamk_f32 v75, v75, 0x3e38aa3b, v234
	ds_read_b64_tr_b16 v[170:171], v227 offset:12288
	s_waitcnt lgkmcnt(14)
	v_fmamk_f32 v76, v76, 0x3e38aa3b, v234
	v_fmamk_f32 v77, v77, 0x3e38aa3b, v234
	v_exp_f32_e32 v70, v70
	ds_read_b64_tr_b16 v[172:173], v227 offset:13312
	s_waitcnt lgkmcnt(14)
	v_exp_f32_e32 v71, v71
	v_exp_f32_e32 v72, v72
	v_exp_f32_e32 v73, v73
	ds_read_b64_tr_b16 v[174:175], v228 offset:12288
	s_waitcnt lgkmcnt(14)
	v_exp_f32_e32 v74, v74
	v_exp_f32_e32 v75, v75
	v_exp_f32_e32 v76, v76
	ds_read_b64_tr_b16 v[176:177], v228 offset:13312
	s_waitcnt lgkmcnt(14)
	v_exp_f32_e32 v77, v77
	v_add_f32_e32 v243, v70, v74
	v_add_f32_e32 v244, v71, v75
	ds_read_b64_tr_b16 v[178:179], v227 offset:14336
	s_waitcnt lgkmcnt(14)
	v_add_f32_e32 v245, v72, v76
	v_add_f32_e32 v246, v73, v77
	v_cvt_pk_bf16_f32 v70, v70, v71
	ds_read_b64_tr_b16 v[180:181], v227 offset:15360
	s_waitcnt lgkmcnt(14)
	v_cvt_pk_bf16_f32 v71, v72, v73
	v_cvt_pk_bf16_f32 v72, v74, v75
	v_cvt_pk_bf16_f32 v73, v76, v77
	ds_read_b64_tr_b16 v[182:183], v228 offset:14336
	s_waitcnt lgkmcnt(14)
	s_waitcnt lgkmcnt(13)
	v_mfma_f32_32x32x16_bf16 v[0:15], v[154:157], v[70:73], v[0:15]
	s_waitcnt lgkmcnt(11)
	v_mfma_f32_32x32x16_bf16 v[16:31], v[158:161], v[70:73], v[16:31]
	v_fmamk_f32 v78, v78, 0x3e38aa3b, v234
	v_fmamk_f32 v79, v79, 0x3e38aa3b, v234
	v_fmamk_f32 v80, v80, 0x3e38aa3b, v234
	ds_read_b64_tr_b16 v[184:185], v228 offset:15360
	v_fmamk_f32 v81, v81, 0x3e38aa3b, v234
	v_fmamk_f32 v82, v82, 0x3e38aa3b, v234
	v_fmamk_f32 v83, v83, 0x3e38aa3b, v234
	v_fmamk_f32 v84, v84, 0x3e38aa3b, v234
	v_fmamk_f32 v85, v85, 0x3e38aa3b, v234
	v_exp_f32_e32 v78, v78
	v_exp_f32_e32 v79, v79
	v_exp_f32_e32 v80, v80
	v_exp_f32_e32 v81, v81
	v_exp_f32_e32 v82, v82
	v_exp_f32_e32 v83, v83
	v_exp_f32_e32 v84, v84
	v_exp_f32_e32 v85, v85
	v_add_f32_e32 v243, v243, v78
	v_add_f32_e32 v244, v244, v79
	v_add_f32_e32 v245, v245, v80
	v_add_f32_e32 v246, v246, v81
	v_add_f32_e32 v243, v243, v82
	v_add_f32_e32 v244, v244, v83
	v_add_f32_e32 v245, v245, v84
	v_add_f32_e32 v246, v246, v85
	v_cvt_pk_bf16_f32 v78, v78, v79
	v_cvt_pk_bf16_f32 v79, v80, v81
	v_cvt_pk_bf16_f32 v80, v82, v83
	v_cvt_pk_bf16_f32 v81, v84, v85
	s_waitcnt lgkmcnt(10)
	v_mfma_f32_32x32x16_bf16 v[0:15], v[162:165], v[78:81], v[0:15]
	s_waitcnt lgkmcnt(8)
	v_mfma_f32_32x32x16_bf16 v[16:31], v[166:169], v[78:81], v[16:31]
	v_fmamk_f32 v86, v86, 0x3e38aa3b, v234
	v_fmamk_f32 v87, v87, 0x3e38aa3b, v234
	v_fmamk_f32 v88, v88, 0x3e38aa3b, v234
	v_fmamk_f32 v89, v89, 0x3e38aa3b, v234
	v_fmamk_f32 v90, v90, 0x3e38aa3b, v234
	v_fmamk_f32 v91, v91, 0x3e38aa3b, v234
	v_fmamk_f32 v92, v92, 0x3e38aa3b, v234
	v_fmamk_f32 v93, v93, 0x3e38aa3b, v234
	v_exp_f32_e32 v86, v86
	v_exp_f32_e32 v87, v87
	v_exp_f32_e32 v88, v88
	v_exp_f32_e32 v89, v89
	v_exp_f32_e32 v90, v90
	v_exp_f32_e32 v91, v91
	v_exp_f32_e32 v92, v92
	v_exp_f32_e32 v93, v93
	v_add_f32_e32 v243, v243, v86
	v_add_f32_e32 v244, v244, v87
	v_add_f32_e32 v245, v245, v88
	v_add_f32_e32 v246, v246, v89
	v_add_f32_e32 v243, v243, v90
	v_add_f32_e32 v244, v244, v91
	v_add_f32_e32 v245, v245, v92
	v_add_f32_e32 v246, v246, v93
	v_cvt_pk_bf16_f32 v86, v86, v87
	v_cvt_pk_bf16_f32 v87, v88, v89
	v_cvt_pk_bf16_f32 v88, v90, v91
	v_cvt_pk_bf16_f32 v89, v92, v93
	s_waitcnt lgkmcnt(6)
	v_mfma_f32_32x32x16_bf16 v[0:15], v[170:173], v[86:89], v[0:15]
	s_waitcnt lgkmcnt(4)
	v_mfma_f32_32x32x16_bf16 v[16:31], v[174:177], v[86:89], v[16:31]
	v_fmamk_f32 v94, v94, 0x3e38aa3b, v234
	v_fmamk_f32 v95, v95, 0x3e38aa3b, v234
	v_fmamk_f32 v96, v96, 0x3e38aa3b, v234
	v_fmamk_f32 v97, v97, 0x3e38aa3b, v234
	v_fmamk_f32 v98, v98, 0x3e38aa3b, v234
	v_fmamk_f32 v99, v99, 0x3e38aa3b, v234
	v_fmamk_f32 v100, v100, 0x3e38aa3b, v234
	v_fmamk_f32 v101, v101, 0x3e38aa3b, v234
	v_exp_f32_e32 v94, v94
	v_exp_f32_e32 v95, v95
	v_exp_f32_e32 v96, v96
	v_exp_f32_e32 v97, v97
	v_exp_f32_e32 v98, v98
	v_exp_f32_e32 v99, v99
	v_exp_f32_e32 v100, v100
	v_exp_f32_e32 v101, v101
	v_add_f32_e32 v243, v243, v94
	v_add_f32_e32 v244, v244, v95
	v_add_f32_e32 v245, v245, v96
	v_add_f32_e32 v246, v246, v97
	v_add_f32_e32 v243, v243, v98
	v_add_f32_e32 v244, v244, v99
	v_add_f32_e32 v245, v245, v100
	v_add_f32_e32 v246, v246, v101
	v_cvt_pk_bf16_f32 v94, v94, v95
	v_cvt_pk_bf16_f32 v95, v96, v97
	v_cvt_pk_bf16_f32 v96, v98, v99
	v_cvt_pk_bf16_f32 v97, v100, v101
	v_add_f32_e32 v243, v243, v244
	v_add_f32_e32 v245, v245, v246
	v_add_f32_e32 v243, v243, v245
	v_fma_f32 v231, v231, v232, v243
	s_waitcnt lgkmcnt(2)
	v_mfma_f32_32x32x16_bf16 v[0:15], v[178:181], v[94:97], v[0:15]
	s_waitcnt lgkmcnt(0)
	v_mfma_f32_32x32x16_bf16 v[16:31], v[182:185], v[94:97], v[16:31]
	s_add_u32 s8, s8, 1
	s_add_u32 s18, s8, 4
	s_min_u32 s18, s18, s11
	s_mul_i32 s18, s18, 0xb2c00
	s_add_u32 s12, s4, s18
	s_addc_u32 s13, s5, 0
	s_add_u32 s19, s8, 2
	s_min_u32 s19, s19, s11
	s_mul_i32 s18, s19, 0xb2c00
	s_add_u32 s14, s4, s18
	s_addc_u32 s15, s5, 0
	s_lshl_b32 s19, s19, 3
	s_add_u32 s16, s6, s19
	s_addc_u32 s17, s7, 0
	global_load_dwordx4 v[198:201], v219, s[16:17]
	s_add_i32 m0, s58, 0x8000
	s_nop 0
	global_load_lds_dwordx4 v222, s[14:15]
	s_cmp_lt_u32 s8, s9
	s_waitcnt vmcnt(4)
	s_barrier
	s_cbranch_scc1 .Lat_loop_2
	s_branch .Lat_epilogue
.Lat_loop_2:
	s_add_i32 m0, s58, 0x4000
	s_nop 0
	global_load_lds_dwordx4 v221, s[12:13]
	s_cmp_lt_u32 s8, s10
	s_cbranch_scc1 .Lat_full_2
	s_cmp_eq_u32 s8, s10
	s_cbranch_scc1 .Lat_last_2
.Lat_idle_2:
	s_add_u32 s8, s8, 1
	s_add_u32 s18, s8, 4
	s_min_u32 s18, s18, s11
	s_mul_i32 s18, s18, 0xb2c00
	s_add_u32 s12, s4, s18
	s_addc_u32 s13, s5, 0
	s_add_u32 s19, s8, 2
	s_min_u32 s19, s19, s11
	s_mul_i32 s18, s19, 0xb2c00
	s_add_u32 s14, s4, s18
	s_addc_u32 s15, s5, 0
	s_add_i32 m0, s58, 0xa000
	s_nop 0
	global_load_lds_dwordx4 v222, s[14:15]
	s_cmp_lt_u32 s8, s9
	s_waitcnt vmcnt(4)
	s_barrier
	s_cbranch_scc1 .Lat_loop_3
	s_branch .Lat_epilogue

.Lat_nors_f2:
	v_fmamk_f32 v34, v34, 0x3e38aa3b, v234
	v_fmamk_f32 v35, v35, 0x3e38aa3b, v234
	s_waitcnt lgkmcnt(7)
	v_mfma_f32_32x32x16_bf16 v[70:85], v[118:121], v[102:105], 0
	ds_read_b64_tr_b16 v[154:155], v227 offset:16384
	ds_read_b64_tr_b16 v[156:157], v227 offset:17408
	v_fmamk_f32 v36, v36, 0x3e38aa3b, v234
	v_fmamk_f32 v37, v37, 0x3e38aa3b, v234
	v_fmamk_f32 v38, v38, 0x3e38aa3b, v234
	v_fmamk_f32 v39, v39, 0x3e38aa3b, v234
	v_fmamk_f32 v40, v40, 0x3e38aa3b, v234
	v_fmamk_f32 v41, v41, 0x3e38aa3b, v234
	v_exp_f32_e32 v34, v34
	v_exp_f32_e32 v35, v35
	v_exp_f32_e32 v36, v36
	v_exp_f32_e32 v37, v37
	v_exp_f32_e32 v38, v38
	v_exp_f32_e32 v39, v39
	s_waitcnt lgkmcnt(8)
	v_mfma_f32_32x32x16_bf16 v[86:101], v[122:125], v[102:105], 0
	ds_read_b64_tr_b16 v[158:159], v228 offset:16384
	ds_read_b64_tr_b16 v[160:161], v228 offset:17408
	v_exp_f32_e32 v40, v40
	v_exp_f32_e32 v41, v41
	v_add_f32_e32 v243, v34, v38
	v_add_f32_e32 v244, v35, v39
	v_add_f32_e32 v245, v36, v40
	v_add_f32_e32 v246, v37, v41
	v_cvt_pk_bf16_f32 v34, v34, v35
	v_cvt_pk_bf16_f32 v35, v36, v37
	v_cvt_pk_bf16_f32 v36, v38, v39
	v_cvt_pk_bf16_f32 v37, v40, v41
	v_fmamk_f32 v42, v42, 0x3e38aa3b, v234
	v_fmamk_f32 v43, v43, 0x3e38aa3b, v234
	s_waitcnt lgkmcnt(9)
	v_mfma_f32_32x32x16_bf16 v[70:85], v[126:129], v[106:109], v[70:85]
	ds_read_b64_tr_b16 v[162:163], v227 offset:18432
	ds_read_b64_tr_b16 v[164:165], v227 offset:19456
	v_fmamk_f32 v44, v44, 0x3e38aa3b, v234
	v_fmamk_f32 v45, v45, 0x3e38aa3b, v234
	v_fmamk_f32 v46, v46, 0x3e38aa3b, v234
	v_fmamk_f32 v47, v47, 0x3e38aa3b, v234
	v_fmamk_f32 v48, v48, 0x3e38aa3b, v234
	v_fmamk_f32 v49, v49, 0x3e38aa3b, v234
	v_exp_f32_e32 v42, v42
	v_exp_f32_e32 v43, v43
	v_exp_f32_e32 v44, v44
	v_exp_f32_e32 v45, v45
	v_exp_f32_e32 v46, v46
	v_exp_f32_e32 v47, v47
	s_waitcnt lgkmcnt(10)
	v_mfma_f32_32x32x16_bf16 v[86:101], v[130:133], v[106:109], v[86:101]
	ds_read_b64_tr_b16 v[166:167], v228 offset:18432
	ds_read_b64_tr_b16 v[168:169], v228 offset:19456
	v_exp_f32_e32 v48, v48
	v_exp_f32_e32 v49, v49
	v_add_f32_e32 v243, v243, v42
	v_add_f32_e32 v244, v244, v43
	v_add_f32_e32 v245, v245, v44
	v_add_f32_e32 v246, v246, v45
	v_add_f32_e32 v243, v243, v46
	v_add_f32_e32 v244, v244, v47
	v_add_f32_e32 v245, v245, v48
	v_add_f32_e32 v246, v246, v49
	v_cvt_pk_bf16_f32 v42, v42, v43
	v_cvt_pk_bf16_f32 v43, v44, v45
	s_waitcnt lgkmcnt(11)
	v_mfma_f32_32x32x16_bf16 v[70:85], v[134:137], v[110:113], v[70:85]
	ds_read_b64_tr_b16 v[170:171], v227 offset:20480
	ds_read_b64_tr_b16 v[172:173], v227 offset:21504
	v_cvt_pk_bf16_f32 v44, v46, v47
	v_cvt_pk_bf16_f32 v45, v48, v49
	v_fmamk_f32 v50, v50, 0x3e38aa3b, v234
	v_fmamk_f32 v51, v51, 0x3e38aa3b, v234
	v_fmamk_f32 v52, v52, 0x3e38aa3b, v234
	v_fmamk_f32 v53, v53, 0x3e38aa3b, v234
	v_fmamk_f32 v54, v54, 0x3e38aa3b, v234
	v_fmamk_f32 v55, v55, 0x3e38aa3b, v234
	v_fmamk_f32 v56, v56, 0x3e38aa3b, v234
	v_fmamk_f32 v57, v57, 0x3e38aa3b, v234
	v_exp_f32_e32 v50, v50
	v_exp_f32_e32 v51, v51
	s_waitcnt lgkmcnt(12)
	v_mfma_f32_32x32x16_bf16 v[86:101], v[138:141], v[110:113], v[86:101]
	ds_read_b64_tr_b16 v[174:175], v228 offset:20480
	ds_read_b64_tr_b16 v[176:177], v228 offset:21504
	v_exp_f32_e32 v52, v52
	v_exp_f32_e32 v53, v53
	v_exp_f32_e32 v54, v54
	v_exp_f32_e32 v55, v55
	v_exp_f32_e32 v56, v56
	v_exp_f32_e32 v57, v57
	v_add_f32_e32 v243, v243, v50
	v_add_f32_e32 v244, v244, v51
	v_add_f32_e32 v245, v245, v52
	v_add_f32_e32 v246, v246, v53
	v_add_f32_e32 v243, v243, v54
	v_add_f32_e32 v244, v244, v55
	s_waitcnt lgkmcnt(13)
	v_mfma_f32_32x32x16_bf16 v[70:85], v[142:145], v[114:117], v[70:85]
	ds_read_b64_tr_b16 v[178:179], v227 offset:22528
	ds_read_b64_tr_b16 v[180:181], v227 offset:23552
	v_add_f32_e32 v245, v245, v56
	v_add_f32_e32 v246, v246, v57
	v_cvt_pk_bf16_f32 v50, v50, v51
	v_cvt_pk_bf16_f32 v51, v52, v53
	v_cvt_pk_bf16_f32 v52, v54, v55
	v_cvt_pk_bf16_f32 v53, v56, v57
	v_fmamk_f32 v58, v58, 0x3e38aa3b, v234
	v_fmamk_f32 v59, v59, 0x3e38aa3b, v234
	v_fmamk_f32 v60, v60, 0x3e38aa3b, v234
	v_fmamk_f32 v61, v61, 0x3e38aa3b, v234
	v_fmamk_f32 v62, v62, 0x3e38aa3b, v234
	v_fmamk_f32 v63, v63, 0x3e38aa3b, v234
	s_waitcnt lgkmcnt(14)
	v_mfma_f32_32x32x16_bf16 v[86:101], v[146:149], v[114:117], v[86:101]
	ds_read_b64_tr_b16 v[182:183], v228 offset:22528
	ds_read_b64_tr_b16 v[184:185], v228 offset:23552
	s_waitcnt lgkmcnt(14)
	v_fmamk_f32 v64, v64, 0x3e38aa3b, v234
	v_fmamk_f32 v65, v65, 0x3e38aa3b, v234
	v_exp_f32_e32 v58, v58
	v_exp_f32_e32 v59, v59
	v_exp_f32_e32 v60, v60
	v_exp_f32_e32 v61, v61
	v_exp_f32_e32 v62, v62
	v_exp_f32_e32 v63, v63
	v_exp_f32_e32 v64, v64
	v_exp_f32_e32 v65, v65
	v_add_f32_e32 v243, v243, v58
	v_add_f32_e32 v244, v244, v59
	v_add_f32_e32 v245, v245, v60
	v_add_f32_e32 v246, v246, v61
	s_waitcnt lgkmcnt(14)
	v_mfma_f32_32x32x16_bf16 v[0:15], v[154:157], v[34:37], v[0:15]
	ds_read_b128 v[118:121], v223 offset:0
	v_add_f32_e32 v243, v243, v62
	v_add_f32_e32 v244, v244, v63
	v_add_f32_e32 v245, v245, v64
	v_add_f32_e32 v246, v246, v65
	v_cvt_pk_bf16_f32 v58, v58, v59
	v_cvt_pk_bf16_f32 v59, v60, v61
	v_cvt_pk_bf16_f32 v60, v62, v63
	v_cvt_pk_bf16_f32 v61, v64, v65
	v_add_f32_e32 v243, v243, v244
	v_add_f32_e32 v245, v245, v246
	v_add_f32_e32 v243, v243, v245
	v_fma_f32 v231, v231, v232, v243
	s_waitcnt lgkmcnt(13)
	v_mfma_f32_32x32x16_bf16 v[16:31], v[158:161], v[34:37], v[16:31]
	ds_read_b128 v[122:125], v223 offset:4096
	v_lshrrev_b32_e32 v249, v229, v204
	v_lshrrev_b32_e32 v250, v229, v205
	v_bfe_i32 v235, v249, 0, 1
	v_bfe_i32 v236, v250, 0, 1
	v_bfe_i32 v237, v249, 1, 1
	v_bfe_i32 v238, v250, 1, 1
	v_bfe_i32 v239, v249, 2, 1
	v_bfe_i32 v240, v250, 2, 1
	v_bfe_i32 v241, v249, 3, 1
	v_bfe_i32 v242, v250, 3, 1
	v_bitop3_b32 v70, v70, s33, v235 bitop3:0xe4
	s_waitcnt lgkmcnt(12)
	v_mfma_f32_32x32x16_bf16 v[0:15], v[162:165], v[42:45], v[0:15]
	ds_read_b128 v[126:129], v224 offset:0
	v_bitop3_b32 v86, v86, s33, v236 bitop3:0xe4
	v_bitop3_b32 v71, v71, s33, v237 bitop3:0xe4
	v_bitop3_b32 v87, v87, s33, v238 bitop3:0xe4
	v_bitop3_b32 v72, v72, s33, v239 bitop3:0xe4
	v_bitop3_b32 v88, v88, s33, v240 bitop3:0xe4
	v_bitop3_b32 v73, v73, s33, v241 bitop3:0xe4
	v_bitop3_b32 v89, v89, s33, v242 bitop3:0xe4
	v_max3_f32 v247, v70, s33, v86
	v_max3_f32 v248, v71, s33, v87
	v_max3_f32 v247, v247, v72, v88
	v_max3_f32 v248, v248, v73, v89
	v_bfe_i32 v235, v249, 8, 1
	s_waitcnt lgkmcnt(11)
	v_mfma_f32_32x32x16_bf16 v[16:31], v[166:169], v[42:45], v[16:31]
	ds_read_b128 v[130:133], v224 offset:4096
	v_bfe_i32 v236, v250, 8, 1
	v_bfe_i32 v237, v249, 9, 1
	v_bfe_i32 v238, v250, 9, 1
	v_bfe_i32 v239, v249, 10, 1
	v_bfe_i32 v240, v250, 10, 1
	v_bfe_i32 v241, v249, 11, 1
	v_bfe_i32 v242, v250, 11, 1
	v_bitop3_b32 v74, v74, s33, v235 bitop3:0xe4
	v_bitop3_b32 v90, v90, s33, v236 bitop3:0xe4
	v_bitop3_b32 v75, v75, s33, v237 bitop3:0xe4
	v_bitop3_b32 v91, v91, s33, v238 bitop3:0xe4
	v_bitop3_b32 v76, v76, s33, v239 bitop3:0xe4
	s_waitcnt lgkmcnt(10)
	v_mfma_f32_32x32x16_bf16 v[0:15], v[170:173], v[50:53], v[0:15]
	ds_read_b128 v[134:137], v225 offset:0
	v_bitop3_b32 v92, v92, s33, v240 bitop3:0xe4
	v_bitop3_b32 v77, v77, s33, v241 bitop3:0xe4
	v_bitop3_b32 v93, v93, s33, v242 bitop3:0xe4
	v_max3_f32 v247, v247, v74, v90
	v_max3_f32 v248, v248, v75, v91
	v_max3_f32 v247, v247, v76, v92
	v_max3_f32 v248, v248, v77, v93
	v_bfe_i32 v235, v249, 16, 1
	v_bfe_i32 v236, v250, 16, 1
	v_bfe_i32 v237, v249, 17, 1
	v_bfe_i32 v238, v250, 17, 1
	v_bfe_i32 v239, v249, 18, 1
	s_waitcnt lgkmcnt(9)
	v_mfma_f32_32x32x16_bf16 v[16:31], v[174:177], v[50:53], v[16:31]
	ds_read_b128 v[138:141], v225 offset:4096
	v_bfe_i32 v240, v250, 18, 1
	v_bfe_i32 v241, v249, 19, 1
	v_bfe_i32 v242, v250, 19, 1
	v_bitop3_b32 v78, v78, s33, v235 bitop3:0xe4
	v_bitop3_b32 v94, v94, s33, v236 bitop3:0xe4
	v_bitop3_b32 v79, v79, s33, v237 bitop3:0xe4
	v_bitop3_b32 v95, v95, s33, v238 bitop3:0xe4
	v_bitop3_b32 v80, v80, s33, v239 bitop3:0xe4
	v_bitop3_b32 v96, v96, s33, v240 bitop3:0xe4
	v_bitop3_b32 v81, v81, s33, v241 bitop3:0xe4
	v_bitop3_b32 v97, v97, s33, v242 bitop3:0xe4
	v_max3_f32 v247, v247, v78, v94
	s_waitcnt lgkmcnt(8)
	v_mfma_f32_32x32x16_bf16 v[0:15], v[178:181], v[58:61], v[0:15]
	ds_read_b128 v[142:145], v226 offset:0
	v_max3_f32 v248, v248, v79, v95
	v_max3_f32 v247, v247, v80, v96
	v_max3_f32 v248, v248, v81, v97
	v_bfe_i32 v235, v249, 24, 1
	v_bfe_i32 v236, v250, 24, 1
	v_bfe_i32 v237, v249, 25, 1
	v_bfe_i32 v238, v250, 25, 1
	v_bfe_i32 v239, v249, 26, 1
	v_bfe_i32 v240, v250, 26, 1
	v_bfe_i32 v241, v249, 27, 1
	v_bfe_i32 v242, v250, 27, 1
	v_bitop3_b32 v82, v82, s33, v235 bitop3:0xe4
	s_waitcnt lgkmcnt(7)
	v_mfma_f32_32x32x16_bf16 v[16:31], v[182:185], v[58:61], v[16:31]
	ds_read_b128 v[146:149], v226 offset:4096
	v_bitop3_b32 v98, v98, s33, v236 bitop3:0xe4
	v_bitop3_b32 v83, v83, s33, v237 bitop3:0xe4
	v_bitop3_b32 v99, v99, s33, v238 bitop3:0xe4
	v_bitop3_b32 v84, v84, s33, v239 bitop3:0xe4
	v_bitop3_b32 v100, v100, s33, v240 bitop3:0xe4
	v_bitop3_b32 v85, v85, s33, v241 bitop3:0xe4
	v_bitop3_b32 v101, v101, s33, v242 bitop3:0xe4
	v_max3_f32 v247, v247, v82, v98
	v_max3_f32 v248, v248, v83, v99
	v_max3_f32 v247, v247, v84, v100
	v_max3_f32 v248, v248, v85, v101
	v_max_f32_e32 v247, v247, v248
	v_mov_b32_e32 v248, v247
	s_nop 1
	v_permlane32_swap_b32_e32 v247, v248
	v_max3_f32 v247, v230, v247, v248
	v_cmp_neq_f32_e32 vcc, s33, v247
	s_nop 1
	v_cndmask_b32_e32 v248, 0, v247, vcc
	v_sub_f32_e32 v33, v230, v248
	v_mul_f32_e32 v33, 0x3e38aa3b, v33
	v_exp_f32_e32 v232, v33
	v_mul_f32_e32 v234, 0xbe38aa3b, v248
	v_mov_b32_e32 v230, v247
	s_add_u32 s8, s8, 1
	s_add_u32 s18, s8, 4
	s_min_u32 s18, s18, s11
	s_mul_i32 s18, s18, 0xb2c00
	s_add_u32 s12, s4, s18
	s_addc_u32 s13, s5, 0
	s_add_u32 s19, s8, 2
	s_min_u32 s19, s19, s11
	s_mul_i32 s18, s19, 0xb2c00
	s_add_u32 s14, s4, s18
	s_addc_u32 s15, s5, 0
	s_add_i32 m0, s58, 0xa000
	s_nop 0
	global_load_lds_dwordx4 v222, s[14:15]
	s_cmp_lt_u32 s8, s9
	s_waitcnt vmcnt(4)
	s_barrier
	s_cbranch_scc1 .Lat_loop_3
	s_branch .Lat_epilogue

.Lat_nors_l2:
	v_fmamk_f32 v34, v34, 0x3e38aa3b, v234
	v_fmamk_f32 v35, v35, 0x3e38aa3b, v234
	v_fmamk_f32 v36, v36, 0x3e38aa3b, v234
	ds_read_b64_tr_b16 v[168:169], v228 offset:19456
	s_waitcnt lgkmcnt(14)
	v_fmamk_f32 v37, v37, 0x3e38aa3b, v234
	v_fmamk_f32 v38, v38, 0x3e38aa3b, v234
	v_fmamk_f32 v39, v39, 0x3e38aa3b, v234
	ds_read_b64_tr_b16 v[170:171], v227 offset:20480
	s_waitcnt lgkmcnt(14)
	v_fmamk_f32 v40, v40, 0x3e38aa3b, v234
	v_fmamk_f32 v41, v41, 0x3e38aa3b, v234
	v_exp_f32_e32 v34, v34
	ds_read_b64_tr_b16 v[172:173], v227 offset:21504
	s_waitcnt lgkmcnt(14)
	v_exp_f32_e32 v35, v35
	v_exp_f32_e32 v36, v36
	v_exp_f32_e32 v37, v37
	ds_read_b64_tr_b16 v[174:175], v228 offset:20480
	s_waitcnt lgkmcnt(14)
	v_exp_f32_e32 v38, v38
	v_exp_f32_e32 v39, v39
	v_exp_f32_e32 v40, v40
	ds_read_b64_tr_b16 v[176:177], v228 offset:21504
	s_waitcnt lgkmcnt(14)
	v_exp_f32_e32 v41, v41
	v_add_f32_e32 v243, v34, v38
	v_add_f32_e32 v244, v35, v39
	ds_read_b64_tr_b16 v[178:179], v227 offset:22528
	s_waitcnt lgkmcnt(14)
	v_add_f32_e32 v245, v36, v40
	v_add_f32_e32 v246, v37, v41
	v_cvt_pk_bf16_f32 v34, v34, v35
	ds_read_b64_tr_b16 v[180:181], v227 offset:23552
	s_waitcnt lgkmcnt(14)
	v_cvt_pk_bf16_f32 v35, v36, v37
	v_cvt_pk_bf16_f32 v36, v38, v39
	v_cvt_pk_bf16_f32 v37, v40, v41
	ds_read_b64_tr_b16 v[182:183], v228 offset:22528
	s_waitcnt lgkmcnt(14)
	s_waitcnt lgkmcnt(13)
	v_mfma_f32_32x32x16_bf16 v[0:15], v[154:157], v[34:37], v[0:15]
	s_waitcnt lgkmcnt(11)
	v_mfma_f32_32x32x16_bf16 v[16:31], v[158:161], v[34:37], v[16:31]
	v_fmamk_f32 v42, v42, 0x3e38aa3b, v234
	v_fmamk_f32 v43, v43, 0x3e38aa3b, v234
	v_fmamk_f32 v44, v44, 0x3e38aa3b, v234
	ds_read_b64_tr_b16 v[184:185], v228 offset:23552
	v_fmamk_f32 v45, v45, 0x3e38aa3b, v234
	v_fmamk_f32 v46, v46, 0x3e38aa3b, v234
	v_fmamk_f32 v47, v47, 0x3e38aa3b, v234
	v_fmamk_f32 v48, v48, 0x3e38aa3b, v234
	v_fmamk_f32 v49, v49, 0x3e38aa3b, v234
	v_exp_f32_e32 v42, v42
	v_exp_f32_e32 v43, v43
	v_exp_f32_e32 v44, v44
	v_exp_f32_e32 v45, v45
	v_exp_f32_e32 v46, v46
	v_exp_f32_e32 v47, v47
	v_exp_f32_e32 v48, v48
	v_exp_f32_e32 v49, v49
	v_add_f32_e32 v243, v243, v42
	v_add_f32_e32 v244, v244, v43
	v_add_f32_e32 v245, v245, v44
	v_add_f32_e32 v246, v246, v45
	v_add_f32_e32 v243, v243, v46
	v_add_f32_e32 v244, v244, v47
	v_add_f32_e32 v245, v245, v48
	v_add_f32_e32 v246, v246, v49
	v_cvt_pk_bf16_f32 v42, v42, v43
	v_cvt_pk_bf16_f32 v43, v44, v45
	v_cvt_pk_bf16_f32 v44, v46, v47
	v_cvt_pk_bf16_f32 v45, v48, v49
	s_waitcnt lgkmcnt(10)
	v_mfma_f32_32x32x16_bf16 v[0:15], v[162:165], v[42:45], v[0:15]
	s_waitcnt lgkmcnt(8)
	v_mfma_f32_32x32x16_bf16 v[16:31], v[166:169], v[42:45], v[16:31]
	v_fmamk_f32 v50, v50, 0x3e38aa3b, v234
	v_fmamk_f32 v51, v51, 0x3e38aa3b, v234
	v_fmamk_f32 v52, v52, 0x3e38aa3b, v234
	v_fmamk_f32 v53, v53, 0x3e38aa3b, v234
	v_fmamk_f32 v54, v54, 0x3e38aa3b, v234
	v_fmamk_f32 v55, v55, 0x3e38aa3b, v234
	v_fmamk_f32 v56, v56, 0x3e38aa3b, v234
	v_fmamk_f32 v57, v57, 0x3e38aa3b, v234
	v_exp_f32_e32 v50, v50
	v_exp_f32_e32 v51, v51
	v_exp_f32_e32 v52, v52
	v_exp_f32_e32 v53, v53
	v_exp_f32_e32 v54, v54
	v_exp_f32_e32 v55, v55
	v_exp_f32_e32 v56, v56
	v_exp_f32_e32 v57, v57
	v_add_f32_e32 v243, v243, v50
	v_add_f32_e32 v244, v244, v51
	v_add_f32_e32 v245, v245, v52
	v_add_f32_e32 v246, v246, v53
	v_add_f32_e32 v243, v243, v54
	v_add_f32_e32 v244, v244, v55
	v_add_f32_e32 v245, v245, v56
	v_add_f32_e32 v246, v246, v57
	v_cvt_pk_bf16_f32 v50, v50, v51
	v_cvt_pk_bf16_f32 v51, v52, v53
	v_cvt_pk_bf16_f32 v52, v54, v55
	v_cvt_pk_bf16_f32 v53, v56, v57
	s_waitcnt lgkmcnt(6)
	v_mfma_f32_32x32x16_bf16 v[0:15], v[170:173], v[50:53], v[0:15]
	s_waitcnt lgkmcnt(4)
	v_mfma_f32_32x32x16_bf16 v[16:31], v[174:177], v[50:53], v[16:31]
	v_fmamk_f32 v58, v58, 0x3e38aa3b, v234
	v_fmamk_f32 v59, v59, 0x3e38aa3b, v234
	v_fmamk_f32 v60, v60, 0x3e38aa3b, v234
	v_fmamk_f32 v61, v61, 0x3e38aa3b, v234
	v_fmamk_f32 v62, v62, 0x3e38aa3b, v234
	v_fmamk_f32 v63, v63, 0x3e38aa3b, v234
	v_fmamk_f32 v64, v64, 0x3e38aa3b, v234
	v_fmamk_f32 v65, v65, 0x3e38aa3b, v234
	v_exp_f32_e32 v58, v58
	v_exp_f32_e32 v59, v59
	v_exp_f32_e32 v60, v60
	v_exp_f32_e32 v61, v61
	v_exp_f32_e32 v62, v62
	v_exp_f32_e32 v63, v63
	v_exp_f32_e32 v64, v64
	v_exp_f32_e32 v65, v65
	v_add_f32_e32 v243, v243, v58
	v_add_f32_e32 v244, v244, v59
	v_add_f32_e32 v245, v245, v60
	v_add_f32_e32 v246, v246, v61
	v_add_f32_e32 v243, v243, v62
	v_add_f32_e32 v244, v244, v63
	v_add_f32_e32 v245, v245, v64
	v_add_f32_e32 v246, v246, v65
	v_cvt_pk_bf16_f32 v58, v58, v59
	v_cvt_pk_bf16_f32 v59, v60, v61
	v_cvt_pk_bf16_f32 v60, v62, v63
	v_cvt_pk_bf16_f32 v61, v64, v65
	v_add_f32_e32 v243, v243, v244
	v_add_f32_e32 v245, v245, v246
	v_add_f32_e32 v243, v243, v245
	v_fma_f32 v231, v231, v232, v243
	s_waitcnt lgkmcnt(2)
	v_mfma_f32_32x32x16_bf16 v[0:15], v[178:181], v[58:61], v[0:15]
	s_waitcnt lgkmcnt(0)
	v_mfma_f32_32x32x16_bf16 v[16:31], v[182:185], v[58:61], v[16:31]
	s_add_u32 s8, s8, 1
	s_add_u32 s18, s8, 4
	s_min_u32 s18, s18, s11
	s_mul_i32 s18, s18, 0xb2c00
	s_add_u32 s12, s4, s18
	s_addc_u32 s13, s5, 0
	s_add_u32 s19, s8, 2
	s_min_u32 s19, s19, s11
	s_mul_i32 s18, s19, 0xb2c00
	s_add_u32 s14, s4, s18
	s_addc_u32 s15, s5, 0
	s_add_i32 m0, s58, 0xa000
	s_nop 0
	global_load_lds_dwordx4 v222, s[14:15]
	s_cmp_lt_u32 s8, s9
	s_waitcnt vmcnt(4)
	s_barrier
	s_cbranch_scc1 .Lat_loop_3
	s_branch .Lat_epilogue
.Lat_loop_3:
	s_add_i32 m0, s58, 0x6000
	s_nop 0
	global_load_lds_dwordx4 v221, s[12:13]
	s_cmp_lt_u32 s8, s10
	s_cbranch_scc1 .Lat_full_3
	s_cmp_eq_u32 s8, s10
	s_cbranch_scc1 .Lat_last_3
.Lat_idle_3:
	s_add_u32 s8, s8, 1
	s_add_u32 s18, s8, 4
	s_min_u32 s18, s18, s11
	s_mul_i32 s18, s18, 0xb2c00
	s_add_u32 s12, s4, s18
	s_addc_u32 s13, s5, 0
	s_add_u32 s19, s8, 2
	s_min_u32 s19, s19, s11
	s_mul_i32 s18, s19, 0xb2c00
	s_add_u32 s14, s4, s18
	s_addc_u32 s15, s5, 0
	s_lshl_b32 s19, s19, 3
	s_add_u32 s16, s6, s19
	s_addc_u32 s17, s7, 0
	global_load_dwordx4 v[202:205], v219, s[16:17]
	s_add_i32 m0, s58, 0xc000
	s_nop 0
	global_load_lds_dwordx4 v222, s[14:15]
	s_cmp_lt_u32 s8, s9
	s_waitcnt vmcnt(4)
	s_barrier
	s_cbranch_scc1 .Lat_loop_0
	s_branch .Lat_epilogue

.Lat_nors_f3:
	v_fmamk_f32 v70, v70, 0x3e38aa3b, v234
	v_fmamk_f32 v71, v71, 0x3e38aa3b, v234
	s_waitcnt lgkmcnt(7)
	v_mfma_f32_32x32x16_bf16 v[34:49], v[118:121], v[102:105], 0
	ds_read_b64_tr_b16 v[154:155], v227 offset:24576
	ds_read_b64_tr_b16 v[156:157], v227 offset:25600
	v_fmamk_f32 v72, v72, 0x3e38aa3b, v234
	v_fmamk_f32 v73, v73, 0x3e38aa3b, v234
	v_fmamk_f32 v74, v74, 0x3e38aa3b, v234
	v_fmamk_f32 v75, v75, 0x3e38aa3b, v234
	v_fmamk_f32 v76, v76, 0x3e38aa3b, v234
	v_fmamk_f32 v77, v77, 0x3e38aa3b, v234
	v_exp_f32_e32 v70, v70
	v_exp_f32_e32 v71, v71
	v_exp_f32_e32 v72, v72
	v_exp_f32_e32 v73, v73
	v_exp_f32_e32 v74, v74
	v_exp_f32_e32 v75, v75
	s_waitcnt lgkmcnt(8)
	v_mfma_f32_32x32x16_bf16 v[50:65], v[122:125], v[102:105], 0
	ds_read_b64_tr_b16 v[158:159], v228 offset:24576
	ds_read_b64_tr_b16 v[160:161], v228 offset:25600
	v_exp_f32_e32 v76, v76
	v_exp_f32_e32 v77, v77
	v_add_f32_e32 v243, v70, v74
	v_add_f32_e32 v244, v71, v75
	v_add_f32_e32 v245, v72, v76
	v_add_f32_e32 v246, v73, v77
	v_cvt_pk_bf16_f32 v70, v70, v71
	v_cvt_pk_bf16_f32 v71, v72, v73
	v_cvt_pk_bf16_f32 v72, v74, v75
	v_cvt_pk_bf16_f32 v73, v76, v77
	v_fmamk_f32 v78, v78, 0x3e38aa3b, v234
	v_fmamk_f32 v79, v79, 0x3e38aa3b, v234
	s_waitcnt lgkmcnt(9)
	v_mfma_f32_32x32x16_bf16 v[34:49], v[126:129], v[106:109], v[34:49]
	ds_read_b64_tr_b16 v[162:163], v227 offset:26624
	ds_read_b64_tr_b16 v[164:165], v227 offset:27648
	v_fmamk_f32 v80, v80, 0x3e38aa3b, v234
	v_fmamk_f32 v81, v81, 0x3e38aa3b, v234
	v_fmamk_f32 v82, v82, 0x3e38aa3b, v234
	v_fmamk_f32 v83, v83, 0x3e38aa3b, v234
	v_fmamk_f32 v84, v84, 0x3e38aa3b, v234
	v_fmamk_f32 v85, v85, 0x3e38aa3b, v234
	v_exp_f32_e32 v78, v78
	v_exp_f32_e32 v79, v79
	v_exp_f32_e32 v80, v80
	v_exp_f32_e32 v81, v81
	v_exp_f32_e32 v82, v82
	v_exp_f32_e32 v83, v83
	s_waitcnt lgkmcnt(10)
	v_mfma_f32_32x32x16_bf16 v[50:65], v[130:133], v[106:109], v[50:65]
	ds_read_b64_tr_b16 v[166:167], v228 offset:26624
	ds_read_b64_tr_b16 v[168:169], v228 offset:27648
	v_exp_f32_e32 v84, v84
	v_exp_f32_e32 v85, v85
	v_add_f32_e32 v243, v243, v78
	v_add_f32_e32 v244, v244, v79
	v_add_f32_e32 v245, v245, v80
	v_add_f32_e32 v246, v246, v81
	v_add_f32_e32 v243, v243, v82
	v_add_f32_e32 v244, v244, v83
	v_add_f32_e32 v245, v245, v84
	v_add_f32_e32 v246, v246, v85
	v_cvt_pk_bf16_f32 v78, v78, v79
	v_cvt_pk_bf16_f32 v79, v80, v81
	s_waitcnt lgkmcnt(11)
	v_mfma_f32_32x32x16_bf16 v[34:49], v[134:137], v[110:113], v[34:49]
	ds_read_b64_tr_b16 v[170:171], v227 offset:28672
	ds_read_b64_tr_b16 v[172:173], v227 offset:29696
	v_cvt_pk_bf16_f32 v80, v82, v83
	v_cvt_pk_bf16_f32 v81, v84, v85
	v_fmamk_f32 v86, v86, 0x3e38aa3b, v234
	v_fmamk_f32 v87, v87, 0x3e38aa3b, v234
	v_fmamk_f32 v88, v88, 0x3e38aa3b, v234
	v_fmamk_f32 v89, v89, 0x3e38aa3b, v234
	v_fmamk_f32 v90, v90, 0x3e38aa3b, v234
	v_fmamk_f32 v91, v91, 0x3e38aa3b, v234
	v_fmamk_f32 v92, v92, 0x3e38aa3b, v234
	v_fmamk_f32 v93, v93, 0x3e38aa3b, v234
	v_exp_f32_e32 v86, v86
	v_exp_f32_e32 v87, v87
	s_waitcnt lgkmcnt(12)
	v_mfma_f32_32x32x16_bf16 v[50:65], v[138:141], v[110:113], v[50:65]
	ds_read_b64_tr_b16 v[174:175], v228 offset:28672
	ds_read_b64_tr_b16 v[176:177], v228 offset:29696
	v_exp_f32_e32 v88, v88
	v_exp_f32_e32 v89, v89
	v_exp_f32_e32 v90, v90
	v_exp_f32_e32 v91, v91
	v_exp_f32_e32 v92, v92
	v_exp_f32_e32 v93, v93
	v_add_f32_e32 v243, v243, v86
	v_add_f32_e32 v244, v244, v87
	v_add_f32_e32 v245, v245, v88
	v_add_f32_e32 v246, v246, v89
	v_add_f32_e32 v243, v243, v90
	v_add_f32_e32 v244, v244, v91
	s_waitcnt lgkmcnt(13)
	v_mfma_f32_32x32x16_bf16 v[34:49], v[142:145], v[114:117], v[34:49]
	ds_read_b64_tr_b16 v[178:179], v227 offset:30720
	ds_read_b64_tr_b16 v[180:181], v227 offset:31744
	v_add_f32_e32 v245, v245, v92
	v_add_f32_e32 v246, v246, v93
	v_cvt_pk_bf16_f32 v86, v86, v87
	v_cvt_pk_bf16_f32 v87, v88, v89
	v_cvt_pk_bf16_f32 v88, v90, v91
	v_cvt_pk_bf16_f32 v89, v92, v93
	v_fmamk_f32 v94, v94, 0x3e38aa3b, v234
	v_fmamk_f32 v95, v95, 0x3e38aa3b, v234
	v_fmamk_f32 v96, v96, 0x3e38aa3b, v234
	v_fmamk_f32 v97, v97, 0x3e38aa3b, v234
	v_fmamk_f32 v98, v98, 0x3e38aa3b, v234
	v_fmamk_f32 v99, v99, 0x3e38aa3b, v234
	s_waitcnt lgkmcnt(14)
	v_mfma_f32_32x32x16_bf16 v[50:65], v[146:149], v[114:117], v[50:65]
	ds_read_b64_tr_b16 v[182:183], v228 offset:30720
	ds_read_b64_tr_b16 v[184:185], v228 offset:31744
	s_waitcnt lgkmcnt(14)
	v_fmamk_f32 v100, v100, 0x3e38aa3b, v234
	v_fmamk_f32 v101, v101, 0x3e38aa3b, v234
	v_exp_f32_e32 v94, v94
	v_exp_f32_e32 v95, v95
	v_exp_f32_e32 v96, v96
	v_exp_f32_e32 v97, v97
	v_exp_f32_e32 v98, v98
	v_exp_f32_e32 v99, v99
	v_exp_f32_e32 v100, v100
	v_exp_f32_e32 v101, v101
	v_add_f32_e32 v243, v243, v94
	v_add_f32_e32 v244, v244, v95
	v_add_f32_e32 v245, v245, v96
	v_add_f32_e32 v246, v246, v97
	s_waitcnt lgkmcnt(14)
	v_mfma_f32_32x32x16_bf16 v[0:15], v[154:157], v[70:73], v[0:15]
	ds_read_b128 v[118:121], v223 offset:8192
	v_add_f32_e32 v243, v243, v98
	v_add_f32_e32 v244, v244, v99
	v_add_f32_e32 v245, v245, v100
	v_add_f32_e32 v246, v246, v101
	v_cvt_pk_bf16_f32 v94, v94, v95
	v_cvt_pk_bf16_f32 v95, v96, v97
	v_cvt_pk_bf16_f32 v96, v98, v99
	v_cvt_pk_bf16_f32 v97, v100, v101
	v_add_f32_e32 v243, v243, v244
	v_add_f32_e32 v245, v245, v246
	v_add_f32_e32 v243, v243, v245
	v_fma_f32 v231, v231, v232, v243
	s_waitcnt lgkmcnt(13)
	v_mfma_f32_32x32x16_bf16 v[16:31], v[158:161], v[70:73], v[16:31]
	ds_read_b128 v[122:125], v223 offset:12288
	s_waitcnt vmcnt(4)
	v_lshrrev_b32_e32 v249, v229, v198
	v_lshrrev_b32_e32 v250, v229, v199
	v_bfe_i32 v235, v249, 0, 1
	v_bfe_i32 v236, v250, 0, 1
	v_bfe_i32 v237, v249, 1, 1
	v_bfe_i32 v238, v250, 1, 1
	v_bfe_i32 v239, v249, 2, 1
	v_bfe_i32 v240, v250, 2, 1
	v_bfe_i32 v241, v249, 3, 1
	v_bfe_i32 v242, v250, 3, 1
	v_bitop3_b32 v34, v34, s33, v235 bitop3:0xe4
	s_waitcnt lgkmcnt(12)
	v_mfma_f32_32x32x16_bf16 v[0:15], v[162:165], v[78:81], v[0:15]
	ds_read_b128 v[126:129], v224 offset:8192
	v_bitop3_b32 v50, v50, s33, v236 bitop3:0xe4
	v_bitop3_b32 v35, v35, s33, v237 bitop3:0xe4
	v_bitop3_b32 v51, v51, s33, v238 bitop3:0xe4
	v_bitop3_b32 v36, v36, s33, v239 bitop3:0xe4
	v_bitop3_b32 v52, v52, s33, v240 bitop3:0xe4
	v_bitop3_b32 v37, v37, s33, v241 bitop3:0xe4
	v_bitop3_b32 v53, v53, s33, v242 bitop3:0xe4
	v_max3_f32 v247, v34, s33, v50
	v_max3_f32 v248, v35, s33, v51
	v_max3_f32 v247, v247, v36, v52
	v_max3_f32 v248, v248, v37, v53
	v_bfe_i32 v235, v249, 8, 1
	s_waitcnt lgkmcnt(11)
	v_mfma_f32_32x32x16_bf16 v[16:31], v[166:169], v[78:81], v[16:31]
	ds_read_b128 v[130:133], v224 offset:12288
	v_bfe_i32 v236, v250, 8, 1
	v_bfe_i32 v237, v249, 9, 1
	v_bfe_i32 v238, v250, 9, 1
	v_bfe_i32 v239, v249, 10, 1
	v_bfe_i32 v240, v250, 10, 1
	v_bfe_i32 v241, v249, 11, 1
	v_bfe_i32 v242, v250, 11, 1
	v_bitop3_b32 v38, v38, s33, v235 bitop3:0xe4
	v_bitop3_b32 v54, v54, s33, v236 bitop3:0xe4
	v_bitop3_b32 v39, v39, s33, v237 bitop3:0xe4
	v_bitop3_b32 v55, v55, s33, v238 bitop3:0xe4
	v_bitop3_b32 v40, v40, s33, v239 bitop3:0xe4
	s_waitcnt lgkmcnt(10)
	v_mfma_f32_32x32x16_bf16 v[0:15], v[170:173], v[86:89], v[0:15]
	ds_read_b128 v[134:137], v225 offset:8192
	v_bitop3_b32 v56, v56, s33, v240 bitop3:0xe4
	v_bitop3_b32 v41, v41, s33, v241 bitop3:0xe4
	v_bitop3_b32 v57, v57, s33, v242 bitop3:0xe4
	v_max3_f32 v247, v247, v38, v54
	v_max3_f32 v248, v248, v39, v55
	v_max3_f32 v247, v247, v40, v56
	v_max3_f32 v248, v248, v41, v57
	v_bfe_i32 v235, v249, 16, 1
	v_bfe_i32 v236, v250, 16, 1
	v_bfe_i32 v237, v249, 17, 1
	v_bfe_i32 v238, v250, 17, 1
	v_bfe_i32 v239, v249, 18, 1
	s_waitcnt lgkmcnt(9)
	v_mfma_f32_32x32x16_bf16 v[16:31], v[174:177], v[86:89], v[16:31]
	ds_read_b128 v[138:141], v225 offset:12288
	v_bfe_i32 v240, v250, 18, 1
	v_bfe_i32 v241, v249, 19, 1
	v_bfe_i32 v242, v250, 19, 1
	v_bitop3_b32 v42, v42, s33, v235 bitop3:0xe4
	v_bitop3_b32 v58, v58, s33, v236 bitop3:0xe4
	v_bitop3_b32 v43, v43, s33, v237 bitop3:0xe4
	v_bitop3_b32 v59, v59, s33, v238 bitop3:0xe4
	v_bitop3_b32 v44, v44, s33, v239 bitop3:0xe4
	v_bitop3_b32 v60, v60, s33, v240 bitop3:0xe4
	v_bitop3_b32 v45, v45, s33, v241 bitop3:0xe4
	v_bitop3_b32 v61, v61, s33, v242 bitop3:0xe4
	v_max3_f32 v247, v247, v42, v58
	s_waitcnt lgkmcnt(8)
	v_mfma_f32_32x32x16_bf16 v[0:15], v[178:181], v[94:97], v[0:15]
	ds_read_b128 v[142:145], v226 offset:8192
	v_max3_f32 v248, v248, v43, v59
	v_max3_f32 v247, v247, v44, v60
	v_max3_f32 v248, v248, v45, v61
	v_bfe_i32 v235, v249, 24, 1
	v_bfe_i32 v236, v250, 24, 1
	v_bfe_i32 v237, v249, 25, 1
	v_bfe_i32 v238, v250, 25, 1
	v_bfe_i32 v239, v249, 26, 1
	v_bfe_i32 v240, v250, 26, 1
	v_bfe_i32 v241, v249, 27, 1
	v_bfe_i32 v242, v250, 27, 1
	v_bitop3_b32 v46, v46, s33, v235 bitop3:0xe4
	s_waitcnt lgkmcnt(7)
	v_mfma_f32_32x32x16_bf16 v[16:31], v[182:185], v[94:97], v[16:31]
	ds_read_b128 v[146:149], v226 offset:12288
	v_bitop3_b32 v62, v62, s33, v236 bitop3:0xe4
	v_bitop3_b32 v47, v47, s33, v237 bitop3:0xe4
	v_bitop3_b32 v63, v63, s33, v238 bitop3:0xe4
	v_bitop3_b32 v48, v48, s33, v239 bitop3:0xe4
	v_bitop3_b32 v64, v64, s33, v240 bitop3:0xe4
	v_bitop3_b32 v49, v49, s33, v241 bitop3:0xe4
	v_bitop3_b32 v65, v65, s33, v242 bitop3:0xe4
	v_max3_f32 v247, v247, v46, v62
	v_max3_f32 v248, v248, v47, v63
	v_max3_f32 v247, v247, v48, v64
	v_max3_f32 v248, v248, v49, v65
	v_max_f32_e32 v247, v247, v248
	v_mov_b32_e32 v248, v247
	s_nop 1
	v_permlane32_swap_b32_e32 v247, v248
	v_max3_f32 v247, v230, v247, v248
	v_cmp_neq_f32_e32 vcc, s33, v247
	s_nop 1
	v_cndmask_b32_e32 v248, 0, v247, vcc
	v_sub_f32_e32 v33, v230, v248
	v_mul_f32_e32 v33, 0x3e38aa3b, v33
	v_exp_f32_e32 v232, v33
	v_mul_f32_e32 v234, 0xbe38aa3b, v248
	v_mov_b32_e32 v230, v247
	s_add_u32 s8, s8, 1
	s_add_u32 s18, s8, 4
	s_min_u32 s18, s18, s11
	s_mul_i32 s18, s18, 0xb2c00
	s_add_u32 s12, s4, s18
	s_addc_u32 s13, s5, 0
	s_add_u32 s19, s8, 2
	s_min_u32 s19, s19, s11
	s_mul_i32 s18, s19, 0xb2c00
	s_add_u32 s14, s4, s18
	s_addc_u32 s15, s5, 0
	s_lshl_b32 s19, s19, 3
	s_add_u32 s16, s6, s19
	s_addc_u32 s17, s7, 0
	global_load_dwordx4 v[202:205], v219, s[16:17]
	s_add_i32 m0, s58, 0xc000
	s_nop 0
	global_load_lds_dwordx4 v222, s[14:15]
	s_cmp_lt_u32 s8, s9
	s_waitcnt vmcnt(4)
	s_barrier
	s_cbranch_scc1 .Lat_loop_0
	s_branch .Lat_epilogue

.Lat_nors_l3:
	v_fmamk_f32 v70, v70, 0x3e38aa3b, v234
	v_fmamk_f32 v71, v71, 0x3e38aa3b, v234
	v_fmamk_f32 v72, v72, 0x3e38aa3b, v234
	ds_read_b64_tr_b16 v[168:169], v228 offset:27648
	s_waitcnt lgkmcnt(14)
	v_fmamk_f32 v73, v73, 0x3e38aa3b, v234
	v_fmamk_f32 v74, v74, 0x3e38aa3b, v234
	v_fmamk_f32 v75, v75, 0x3e38aa3b, v234
	ds_read_b64_tr_b16 v[170:171], v227 offset:28672
	s_waitcnt lgkmcnt(14)
	v_fmamk_f32 v76, v76, 0x3e38aa3b, v234
	v_fmamk_f32 v77, v77, 0x3e38aa3b, v234
	v_exp_f32_e32 v70, v70
	ds_read_b64_tr_b16 v[172:173], v227 offset:29696
	s_waitcnt lgkmcnt(14)
	v_exp_f32_e32 v71, v71
	v_exp_f32_e32 v72, v72
	v_exp_f32_e32 v73, v73
	ds_read_b64_tr_b16 v[174:175], v228 offset:28672
	s_waitcnt lgkmcnt(14)
	v_exp_f32_e32 v74, v74
	v_exp_f32_e32 v75, v75
	v_exp_f32_e32 v76, v76
	ds_read_b64_tr_b16 v[176:177], v228 offset:29696
	s_waitcnt lgkmcnt(14)
	v_exp_f32_e32 v77, v77
	v_add_f32_e32 v243, v70, v74
	v_add_f32_e32 v244, v71, v75
	ds_read_b64_tr_b16 v[178:179], v227 offset:30720
	s_waitcnt lgkmcnt(14)
	v_add_f32_e32 v245, v72, v76
	v_add_f32_e32 v246, v73, v77
	v_cvt_pk_bf16_f32 v70, v70, v71
	ds_read_b64_tr_b16 v[180:181], v227 offset:31744
	s_waitcnt lgkmcnt(14)
	v_cvt_pk_bf16_f32 v71, v72, v73
	v_cvt_pk_bf16_f32 v72, v74, v75
	v_cvt_pk_bf16_f32 v73, v76, v77
	ds_read_b64_tr_b16 v[182:183], v228 offset:30720
	s_waitcnt lgkmcnt(14)
	s_waitcnt lgkmcnt(13)
	v_mfma_f32_32x32x16_bf16 v[0:15], v[154:157], v[70:73], v[0:15]
	s_waitcnt lgkmcnt(11)
	v_mfma_f32_32x32x16_bf16 v[16:31], v[158:161], v[70:73], v[16:31]
	v_fmamk_f32 v78, v78, 0x3e38aa3b, v234
	v_fmamk_f32 v79, v79, 0x3e38aa3b, v234
	v_fmamk_f32 v80, v80, 0x3e38aa3b, v234
	ds_read_b64_tr_b16 v[184:185], v228 offset:31744
	v_fmamk_f32 v81, v81, 0x3e38aa3b, v234
	v_fmamk_f32 v82, v82, 0x3e38aa3b, v234
	v_fmamk_f32 v83, v83, 0x3e38aa3b, v234
	v_fmamk_f32 v84, v84, 0x3e38aa3b, v234
	v_fmamk_f32 v85, v85, 0x3e38aa3b, v234
	v_exp_f32_e32 v78, v78
	v_exp_f32_e32 v79, v79
	v_exp_f32_e32 v80, v80
	v_exp_f32_e32 v81, v81
	v_exp_f32_e32 v82, v82
	v_exp_f32_e32 v83, v83
	v_exp_f32_e32 v84, v84
	v_exp_f32_e32 v85, v85
	v_add_f32_e32 v243, v243, v78
	v_add_f32_e32 v244, v244, v79
	v_add_f32_e32 v245, v245, v80
	v_add_f32_e32 v246, v246, v81
	v_add_f32_e32 v243, v243, v82
	v_add_f32_e32 v244, v244, v83
	v_add_f32_e32 v245, v245, v84
	v_add_f32_e32 v246, v246, v85
	v_cvt_pk_bf16_f32 v78, v78, v79
	v_cvt_pk_bf16_f32 v79, v80, v81
	v_cvt_pk_bf16_f32 v80, v82, v83
	v_cvt_pk_bf16_f32 v81, v84, v85
	s_waitcnt lgkmcnt(10)
	v_mfma_f32_32x32x16_bf16 v[0:15], v[162:165], v[78:81], v[0:15]
	s_waitcnt lgkmcnt(8)
	v_mfma_f32_32x32x16_bf16 v[16:31], v[166:169], v[78:81], v[16:31]
	v_fmamk_f32 v86, v86, 0x3e38aa3b, v234
	v_fmamk_f32 v87, v87, 0x3e38aa3b, v234
	v_fmamk_f32 v88, v88, 0x3e38aa3b, v234
	v_fmamk_f32 v89, v89, 0x3e38aa3b, v234
	v_fmamk_f32 v90, v90, 0x3e38aa3b, v234
	v_fmamk_f32 v91, v91, 0x3e38aa3b, v234
	v_fmamk_f32 v92, v92, 0x3e38aa3b, v234
	v_fmamk_f32 v93, v93, 0x3e38aa3b, v234
	v_exp_f32_e32 v86, v86
	v_exp_f32_e32 v87, v87
	v_exp_f32_e32 v88, v88
	v_exp_f32_e32 v89, v89
	v_exp_f32_e32 v90, v90
	v_exp_f32_e32 v91, v91
	v_exp_f32_e32 v92, v92
	v_exp_f32_e32 v93, v93
	v_add_f32_e32 v243, v243, v86
	v_add_f32_e32 v244, v244, v87
	v_add_f32_e32 v245, v245, v88
	v_add_f32_e32 v246, v246, v89
	v_add_f32_e32 v243, v243, v90
	v_add_f32_e32 v244, v244, v91
	v_add_f32_e32 v245, v245, v92
	v_add_f32_e32 v246, v246, v93
	v_cvt_pk_bf16_f32 v86, v86, v87
	v_cvt_pk_bf16_f32 v87, v88, v89
	v_cvt_pk_bf16_f32 v88, v90, v91
	v_cvt_pk_bf16_f32 v89, v92, v93
	s_waitcnt lgkmcnt(6)
	v_mfma_f32_32x32x16_bf16 v[0:15], v[170:173], v[86:89], v[0:15]
	s_waitcnt lgkmcnt(4)
	v_mfma_f32_32x32x16_bf16 v[16:31], v[174:177], v[86:89], v[16:31]
	v_fmamk_f32 v94, v94, 0x3e38aa3b, v234
	v_fmamk_f32 v95, v95, 0x3e38aa3b, v234
	v_fmamk_f32 v96, v96, 0x3e38aa3b, v234
	v_fmamk_f32 v97, v97, 0x3e38aa3b, v234
	v_fmamk_f32 v98, v98, 0x3e38aa3b, v234
	v_fmamk_f32 v99, v99, 0x3e38aa3b, v234
	v_fmamk_f32 v100, v100, 0x3e38aa3b, v234
	v_fmamk_f32 v101, v101, 0x3e38aa3b, v234
	v_exp_f32_e32 v94, v94
	v_exp_f32_e32 v95, v95
	v_exp_f32_e32 v96, v96
	v_exp_f32_e32 v97, v97
	v_exp_f32_e32 v98, v98
	v_exp_f32_e32 v99, v99
	v_exp_f32_e32 v100, v100
	v_exp_f32_e32 v101, v101
	v_add_f32_e32 v243, v243, v94
	v_add_f32_e32 v244, v244, v95
	v_add_f32_e32 v245, v245, v96
	v_add_f32_e32 v246, v246, v97
	v_add_f32_e32 v243, v243, v98
	v_add_f32_e32 v244, v244, v99
	v_add_f32_e32 v245, v245, v100
	v_add_f32_e32 v246, v246, v101
	v_cvt_pk_bf16_f32 v94, v94, v95
	v_cvt_pk_bf16_f32 v95, v96, v97
	v_cvt_pk_bf16_f32 v96, v98, v99
	v_cvt_pk_bf16_f32 v97, v100, v101
	v_add_f32_e32 v243, v243, v244
	v_add_f32_e32 v245, v245, v246
	v_add_f32_e32 v243, v243, v245
	v_fma_f32 v231, v231, v232, v243
	s_waitcnt lgkmcnt(2)
	v_mfma_f32_32x32x16_bf16 v[0:15], v[178:181], v[94:97], v[0:15]
	s_waitcnt lgkmcnt(0)
	v_mfma_f32_32x32x16_bf16 v[16:31], v[182:185], v[94:97], v[16:31]
	s_add_u32 s8, s8, 1
	s_add_u32 s18, s8, 4
	s_min_u32 s18, s18, s11
	s_mul_i32 s18, s18, 0xb2c00
	s_add_u32 s12, s4, s18
	s_addc_u32 s13, s5, 0
	s_add_u32 s19, s8, 2
	s_min_u32 s19, s19, s11
	s_mul_i32 s18, s19, 0xb2c00
	s_add_u32 s14, s4, s18
	s_addc_u32 s15, s5, 0
	s_lshl_b32 s19, s19, 3
	s_add_u32 s16, s6, s19
	s_addc_u32 s17, s7, 0
	global_load_dwordx4 v[202:205], v219, s[16:17]
	s_add_i32 m0, s58, 0xc000
	s_nop 0
	global_load_lds_dwordx4 v222, s[14:15]
	s_cmp_lt_u32 s8, s9
	s_waitcnt vmcnt(4)
	s_barrier
	s_cbranch_scc1 .Lat_loop_0
	s_branch .Lat_epilogue
